# SSD prompt: B/C conv+silu precomputed once per (batch,group,chunk), shared by the 8 head CUs via workspace + flag
# baseline (speedup 1.0000x reference)
; __device__ __forceinline__ void ssd_prompt_item(const Params& p, int item, const int wv) {
;     ...
;   const int cc = tid & 31, rg = tid >> 5;
;   const int colbc = (cc < 16) ? (1024 + g * 128 + cc * 8) : (1280 + g * 128 + (cc - 16) * 8);
;   const int xc = tid & 7, xr = tid >> 3;
;   const int colx = h * 64 + xc * 8;
;   const int j0 = rg * 8;
;   f32x4 hacc[4];
; #pragma unroll
;   for (int pb = 0; pb < 4; ++pb) hacc[pb] = (f32x4){0.f, 0.f, 0.f, 0.f};
;   u32x4 u[11], ux[5];
;   float a0 = 0.f, a1 = 0.f;
;     ...
;   SSD_PREFETCH(0);
; #pragma unroll 1
;   for (int c = 0; c < 16; ++c) {
;     const int t0 = b * 2048 + c * 128;
;     __syncthreads();
; #pragma unroll
;     for (int pb = 0; pb < 4; ++pb) *(u32x2*)(h_l + (pb * 16 + fr) * 136 + wid * 16 + fq * 4) = pack4(hacc[pb]);
;     if (wid == 0) {
;       dt_l[2 * lane] = a0; dt_l[2 * lane + 1] = a1;
;       float s = (a0 + a1) * Ah;
; #pragma unroll
;       for (int o = 1; o < 64; o <<= 1) { float v = shfl_idx_f(s, (lane - o) & 63); if (lane >= o) s += v; }
;       acum_l[2 * lane + 1] = s; acum_l[2 * lane] = s - a1 * Ah;
;     }
;     {
;       float w[4][8], bias[8];
; #pragma unroll
;       for (int k = 0; k < 4; ++k) { f32x4 w0 = *(const f32x4*)(convw + k * 1536 + colbc), w1 = *(const f32x4*)(convw + k * 1536 + colbc + 4);
;         w[k][0] = w0[0]; w[k][1] = w0[1]; w[k][2] = w0[2]; w[k][3] = w0[3]; w[k][4] = w1[0]; w[k][5] = w1[1]; w[k][6] = w1[2]; w[k][7] = w1[3]; }
;       { f32x4 b0 = *(const f32x4*)(convb + colbc), b1 = *(const f32x4*)(convb + colbc + 4);
;         bias[0] = b0[0]; bias[1] = b0[1]; bias[2] = b0[2]; bias[3] = b0[3]; bias[4] = b1[0]; bias[5] = b1[1]; bias[6] = b1[2]; bias[7] = b1[3]; }
;       unsigned outp[8][4];
; #pragma unroll
;       for (int jj = 0; jj < 8; ++jj) {
;         float o[8];
; #pragma unroll
;         for (int e = 0; e < 8; ++e) o[e] = bias[e];
; #pragma unroll
;         for (int k = 0; k < 4; ++k) {
;           u32x4 uu = u[jj + k];
;           o[0] += w[k][0] * bflo(uu.x); o[1] += w[k][1] * bfhi(uu.x); o[2] += w[k][2] * bflo(uu.y); o[3] += w[k][3] * bfhi(uu.y);
;           o[4] += w[k][4] * bflo(uu.z); o[5] += w[k][5] * bfhi(uu.z); o[6] += w[k][6] * bflo(uu.w); o[7] += w[k][7] * bfhi(uu.w);
;         }
; #pragma unroll
;         for (int e = 0; e < 8; ++e) o[e] = silu_f(o[e]);
; #pragma unroll
.LBB0_566:
	s_lshr_b32 s0, s68, 4
	s_and_b32 s1, s68, 15
	s_lshr_b32 s4, s1, 3
	s_add_u32 s8, s50, 0x72ae000
	s_addc_u32 s9, s51, 0
	s_add_u32 s10, s50, 0xa30e000
	s_addc_u32 s11, s51, 0
	v_readlane_b32 s12, v251, 48
	v_readlane_b32 s13, v251, 49
	v_readlane_b32 s18, v251, 50
	v_readlane_b32 s19, v251, 51
	v_mbcnt_lo_u32_b32 v226, -1, 0
	v_mbcnt_hi_u32_b32 v226, -1, v226
	v_add_u32_e32 v226, s82, v226
	v_and_b32_e32 v227, 31, v226
	v_lshrrev_b32_e32 v228, 5, v226
	v_lshlrev_b32_e32 v228, 3, v228
	v_and_b32_e32 v230, 15, v227
	v_lshlrev_b32_e32 v230, 3, v230
	v_and_b32_e32 v231, 16, v227
	v_lshlrev_b32_e32 v231, 4, v231
	s_lshl_b32 s20, s4, 7
	s_addk_i32 s20, 0x400
	v_add3_u32 v229, v230, v231, s20
	v_mul_u32_u24_e32 v230, 0x600, v228
	v_add_lshl_u32 v232, v230, v229, 1
	v_add_u32_e32 v233, 0x1800, v232
	v_add_u32_e32 v234, 0x3000, v232
	v_add_u32_e32 v235, 0x4800, v232
	v_add_u32_e32 v236, 0x6000, v232
	v_add_u32_e32 v237, 0x7800, v232
	v_lshlrev_b32_e32 v230, 9, v228
	v_add_u32_e32 v230, v230, v229
	v_subrev_u32_e32 v230, 0x400, v230
	v_lshlrev_b32_e32 v238, 1, v230
	v_add_u32_e32 v239, 0x1000, v238
	v_mov_b32_e32 v249, 0
	s_lshl_b32 s20, s0, 21
	v_add_u32_e32 v248, s20, v238
	s_nop 1
	v_lshl_add_u64 v[242:243], v[248:249], 0, s[10:11]
	v_lshlrev_b32_e32 v230, 2, v229
	global_load_dwordx4 v[162:165], v230, s[12:13]
	global_load_dwordx4 v[166:169], v230, s[12:13] offset:16
	v_add_u32_e32 v231, 0x1800, v230
	global_load_dwordx4 v[170:173], v231, s[12:13]
	global_load_dwordx4 v[174:177], v231, s[12:13] offset:16
	v_add_u32_e32 v231, 0x3000, v230
	global_load_dwordx4 v[178:181], v231, s[12:13]
	global_load_dwordx4 v[182:185], v231, s[12:13] offset:16
	v_add_u32_e32 v231, 0x4800, v230
	global_load_dwordx4 v[186:189], v231, s[12:13]
	global_load_dwordx4 v[190:193], v231, s[12:13] offset:16
	global_load_dwordx4 v[194:197], v230, s[18:19]
	global_load_dwordx4 v[198:201], v230, s[18:19] offset:16
	s_and_b32 s5, s1, 7
	s_lshl_b32 s5, s5, 1
	s_add_u32 s6, s5, 2
	v_cmp_le_u32_e64 s[52:53], 3, v228
	v_cmp_le_u32_e64 s[54:55], 2, v228
	v_cmp_le_u32_e64 s[56:57], 1, v228
.Lssdp_unit:
	s_lshl_b32 s7, s0, 11
	s_lshl_b32 s20, s5, 7
	s_add_u32 s7, s7, s20
	s_sub_i32 s20, s7, 3
	s_mulk_i32 s20, 0xc00
	s_ashr_i32 s21, s20, 31
	s_add_u32 s22, s8, s20
	s_addc_u32 s23, s9, s21
	s_lshl_b32 s20, s7, 10
	s_add_u32 s24, s10, s20
	s_addc_u32 s25, s11, 0
	global_load_dwordx4 v[0:3], v232, s[22:23]
	global_load_dwordx4 v[4:7], v232, s[22:23] offset:3072
	global_load_dwordx4 v[8:11], v233, s[22:23]
	global_load_dwordx4 v[12:15], v233, s[22:23] offset:3072
	global_load_dwordx4 v[16:19], v234, s[22:23]
	global_load_dwordx4 v[20:23], v234, s[22:23] offset:3072
	global_load_dwordx4 v[24:27], v235, s[22:23]
	global_load_dwordx4 v[28:31], v235, s[22:23] offset:3072
	global_load_dwordx4 v[32:35], v236, s[22:23]
	global_load_dwordx4 v[36:39], v236, s[22:23] offset:3072
	global_load_dwordx4 v[40:43], v237, s[22:23]
	s_waitcnt vmcnt(0)
	s_cmp_lg_u32 s5, 0
	s_cbranch_scc1 .Lssdp_nomask
	v_cndmask_b32_e64 v0, 0, v0, s[52:53]
	v_cndmask_b32_e64 v1, 0, v1, s[52:53]
	v_cndmask_b32_e64 v2, 0, v2, s[52:53]
	v_cndmask_b32_e64 v3, 0, v3, s[52:53]
	v_cndmask_b32_e64 v4, 0, v4, s[54:55]
	v_cndmask_b32_e64 v5, 0, v5, s[54:55]
	v_cndmask_b32_e64 v6, 0, v6, s[54:55]
	v_cndmask_b32_e64 v7, 0, v7, s[54:55]
	v_cndmask_b32_e64 v8, 0, v8, s[56:57]
	v_cndmask_b32_e64 v9, 0, v9, s[56:57]
	v_cndmask_b32_e64 v10, 0, v10, s[56:57]
	v_cndmask_b32_e64 v11, 0, v11, s[56:57]
.Lssdp_nomask:
	v_lshlrev_b32_e32 v44, 16, v0
	v_and_b32_e32 v45, 0xffff0000, v0
	v_lshlrev_b32_e32 v46, 16, v1
	v_and_b32_e32 v47, 0xffff0000, v1
	v_lshlrev_b32_e32 v48, 16, v2
	v_and_b32_e32 v49, 0xffff0000, v2
	v_lshlrev_b32_e32 v50, 16, v3
	v_and_b32_e32 v51, 0xffff0000, v3
	v_lshlrev_b32_e32 v52, 16, v4
	v_and_b32_e32 v53, 0xffff0000, v4
	v_lshlrev_b32_e32 v54, 16, v5
	v_and_b32_e32 v55, 0xffff0000, v5
	v_lshlrev_b32_e32 v56, 16, v6
	v_and_b32_e32 v57, 0xffff0000, v6
	v_lshlrev_b32_e32 v58, 16, v7
	v_and_b32_e32 v59, 0xffff0000, v7
	v_lshlrev_b32_e32 v60, 16, v8
	v_and_b32_e32 v61, 0xffff0000, v8
	v_lshlrev_b32_e32 v62, 16, v9
	v_and_b32_e32 v63, 0xffff0000, v9
	v_lshlrev_b32_e32 v64, 16, v10
	v_and_b32_e32 v65, 0xffff0000, v10
	v_lshlrev_b32_e32 v66, 16, v11
	v_and_b32_e32 v67, 0xffff0000, v11
	v_lshlrev_b32_e32 v68, 16, v12
	v_and_b32_e32 v69, 0xffff0000, v12
	v_lshlrev_b32_e32 v70, 16, v13
	v_and_b32_e32 v71, 0xffff0000, v13
	v_lshlrev_b32_e32 v72, 16, v14
	v_and_b32_e32 v73, 0xffff0000, v14
	v_lshlrev_b32_e32 v74, 16, v15
	v_and_b32_e32 v75, 0xffff0000, v15
	v_lshlrev_b32_e32 v76, 16, v16
	v_and_b32_e32 v77, 0xffff0000, v16
	v_lshlrev_b32_e32 v78, 16, v17
	v_and_b32_e32 v79, 0xffff0000, v17
	v_lshlrev_b32_e32 v80, 16, v18
	v_and_b32_e32 v81, 0xffff0000, v18
	v_lshlrev_b32_e32 v82, 16, v19
	v_and_b32_e32 v83, 0xffff0000, v19
	v_lshlrev_b32_e32 v84, 16, v20
	v_and_b32_e32 v85, 0xffff0000, v20
	v_lshlrev_b32_e32 v86, 16, v21
	v_and_b32_e32 v87, 0xffff0000, v21
	v_lshlrev_b32_e32 v88, 16, v22
	v_and_b32_e32 v89, 0xffff0000, v22
	v_lshlrev_b32_e32 v90, 16, v23
	v_and_b32_e32 v91, 0xffff0000, v23
	v_lshlrev_b32_e32 v92, 16, v24
	v_and_b32_e32 v93, 0xffff0000, v24
	v_lshlrev_b32_e32 v94, 16, v25
	v_and_b32_e32 v95, 0xffff0000, v25
	v_lshlrev_b32_e32 v96, 16, v26
	v_and_b32_e32 v97, 0xffff0000, v26
	v_lshlrev_b32_e32 v98, 16, v27
	v_and_b32_e32 v99, 0xffff0000, v27
	v_lshlrev_b32_e32 v100, 16, v28
	v_and_b32_e32 v101, 0xffff0000, v28
	v_lshlrev_b32_e32 v102, 16, v29
	v_and_b32_e32 v103, 0xffff0000, v29
	v_lshlrev_b32_e32 v104, 16, v30
	v_and_b32_e32 v105, 0xffff0000, v30
	v_lshlrev_b32_e32 v106, 16, v31
	v_and_b32_e32 v107, 0xffff0000, v31
; __device__ __forceinline__ unsigned cvt_pk(float lo, float hi) { f32x2 v = {lo, hi}; bf16x2_t b = __builtin_convertvector(v, bf16x2_t); return __builtin_bit_cast(unsigned, b); }
; __device__ __forceinline__ float bflo(unsigned w) { return __uint_as_float(w << 16); }
; __device__ __forceinline__ float bfhi(unsigned w) { return __uint_as_float(w & 0xffff0000u); }
; __device__ __forceinline__ float silu_f(float x) { return x * __builtin_amdgcn_rcpf(1.f + __builtin_amdgcn_exp2f(-1.4426950409f * x)); }
; __device__ __forceinline__ void ssd_prompt_item(const Params& p, int item, const int wv) {
;     ...
; #pragma unroll
;       for (int jj = 0; jj < 8; ++jj) {
;         float o[8];
; #pragma unroll
;         for (int e = 0; e < 8; ++e) o[e] = bias[e];
; #pragma unroll
;         for (int k = 0; k < 4; ++k) {
;           u32x4 uu = u[jj + k];
;           o[0] += w[k][0] * bflo(uu.x); o[1] += w[k][1] * bfhi(uu.x); o[2] += w[k][2] * bflo(uu.y); o[3] += w[k][3] * bfhi(uu.y);
;           o[4] += w[k][4] * bflo(uu.z); o[5] += w[k][5] * bfhi(uu.z); o[6] += w[k][6] * bflo(uu.w); o[7] += w[k][7] * bfhi(uu.w);
;         }
; #pragma unroll
;         for (int e = 0; e < 8; ++e) o[e] = silu_f(o[e]);
; #pragma unroll
;         for (int e2 = 0; e2 < 4; ++e2) outp[jj][e2] = cvt_pk(o[2 * e2], o[2 * e2 + 1]);
;       }
	v_lshlrev_b32_e32 v108, 16, v32
	v_and_b32_e32 v109, 0xffff0000, v32
	v_lshlrev_b32_e32 v110, 16, v33
	v_and_b32_e32 v111, 0xffff0000, v33
	v_lshlrev_b32_e32 v112, 16, v34
	v_and_b32_e32 v113, 0xffff0000, v34
	v_lshlrev_b32_e32 v114, 16, v35
	v_and_b32_e32 v115, 0xffff0000, v35
	v_lshlrev_b32_e32 v116, 16, v36
	v_and_b32_e32 v117, 0xffff0000, v36
	v_lshlrev_b32_e32 v118, 16, v37
	v_and_b32_e32 v119, 0xffff0000, v37
	v_lshlrev_b32_e32 v120, 16, v38
	v_and_b32_e32 v121, 0xffff0000, v38
	v_lshlrev_b32_e32 v122, 16, v39
	v_and_b32_e32 v123, 0xffff0000, v39
	v_lshlrev_b32_e32 v124, 16, v40
	v_and_b32_e32 v125, 0xffff0000, v40
	v_lshlrev_b32_e32 v126, 16, v41
	v_and_b32_e32 v127, 0xffff0000, v41
	v_lshlrev_b32_e32 v128, 16, v42
	v_and_b32_e32 v129, 0xffff0000, v42
	v_lshlrev_b32_e32 v130, 16, v43
	v_and_b32_e32 v131, 0xffff0000, v43
	v_pk_fma_f32 v[202:203], v[162:163], v[44:45], v[194:195]
	v_pk_fma_f32 v[204:205], v[164:165], v[46:47], v[196:197]
	v_pk_fma_f32 v[206:207], v[166:167], v[48:49], v[198:199]
	v_pk_fma_f32 v[208:209], v[168:169], v[50:51], v[200:201]
	v_pk_fma_f32 v[202:203], v[170:171], v[52:53], v[202:203]
	v_pk_fma_f32 v[204:205], v[172:173], v[54:55], v[204:205]
	v_pk_fma_f32 v[206:207], v[174:175], v[56:57], v[206:207]
	v_pk_fma_f32 v[208:209], v[176:177], v[58:59], v[208:209]
	v_pk_fma_f32 v[202:203], v[178:179], v[60:61], v[202:203]
	v_pk_fma_f32 v[204:205], v[180:181], v[62:63], v[204:205]
	v_pk_fma_f32 v[206:207], v[182:183], v[64:65], v[206:207]
	v_pk_fma_f32 v[208:209], v[184:185], v[66:67], v[208:209]
	v_pk_fma_f32 v[202:203], v[186:187], v[68:69], v[202:203]
	v_pk_fma_f32 v[204:205], v[188:189], v[70:71], v[204:205]
	v_pk_fma_f32 v[206:207], v[190:191], v[72:73], v[206:207]
	v_pk_fma_f32 v[208:209], v[192:193], v[74:75], v[208:209]
	v_mul_f32_e32 v210, 0xbfb8aa3b, v202
	v_mul_f32_e32 v211, 0xbfb8aa3b, v203
	v_mul_f32_e32 v212, 0xbfb8aa3b, v204
	v_mul_f32_e32 v213, 0xbfb8aa3b, v205
	v_mul_f32_e32 v214, 0xbfb8aa3b, v206
	v_mul_f32_e32 v215, 0xbfb8aa3b, v207
	v_mul_f32_e32 v216, 0xbfb8aa3b, v208
	v_mul_f32_e32 v217, 0xbfb8aa3b, v209
	v_exp_f32_e32 v210, v210
	v_exp_f32_e32 v211, v211
	v_exp_f32_e32 v212, v212
	v_exp_f32_e32 v213, v213
	v_exp_f32_e32 v214, v214
	v_exp_f32_e32 v215, v215
	v_exp_f32_e32 v216, v216
	v_exp_f32_e32 v217, v217
	v_add_f32_e32 v210, 1.0, v210
	v_add_f32_e32 v211, 1.0, v211
	v_add_f32_e32 v212, 1.0, v212
	v_add_f32_e32 v213, 1.0, v213
	v_add_f32_e32 v214, 1.0, v214
	v_add_f32_e32 v215, 1.0, v215
	v_add_f32_e32 v216, 1.0, v216
	v_add_f32_e32 v217, 1.0, v217
	v_rcp_f32_e32 v210, v210
	v_rcp_f32_e32 v211, v211
	v_rcp_f32_e32 v212, v212
	v_rcp_f32_e32 v213, v213
	v_rcp_f32_e32 v214, v214
	v_rcp_f32_e32 v215, v215
	v_rcp_f32_e32 v216, v216
	v_rcp_f32_e32 v217, v217
	v_pk_mul_f32 v[202:203], v[202:203], v[210:211]
	v_pk_mul_f32 v[204:205], v[204:205], v[212:213]
	v_pk_mul_f32 v[206:207], v[206:207], v[214:215]
	v_pk_mul_f32 v[208:209], v[208:209], v[216:217]
	v_cvt_pk_bf16_f32 v218, v202, v203
	v_cvt_pk_bf16_f32 v219, v204, v205
	v_cvt_pk_bf16_f32 v220, v206, v207
	v_cvt_pk_bf16_f32 v221, v208, v209
	global_store_dwordx4 v238, v[218:221], s[24:25]
	v_pk_fma_f32 v[202:203], v[162:163], v[52:53], v[194:195]
	v_pk_fma_f32 v[204:205], v[164:165], v[54:55], v[196:197]
	v_pk_fma_f32 v[206:207], v[166:167], v[56:57], v[198:199]
	v_pk_fma_f32 v[208:209], v[168:169], v[58:59], v[200:201]
	v_pk_fma_f32 v[202:203], v[170:171], v[60:61], v[202:203]
	v_pk_fma_f32 v[204:205], v[172:173], v[62:63], v[204:205]
	v_pk_fma_f32 v[206:207], v[174:175], v[64:65], v[206:207]
	v_pk_fma_f32 v[208:209], v[176:177], v[66:67], v[208:209]
	v_pk_fma_f32 v[202:203], v[178:179], v[68:69], v[202:203]
	v_pk_fma_f32 v[204:205], v[180:181], v[70:71], v[204:205]
	v_pk_fma_f32 v[206:207], v[182:183], v[72:73], v[206:207]
	v_pk_fma_f32 v[208:209], v[184:185], v[74:75], v[208:209]
	v_pk_fma_f32 v[202:203], v[186:187], v[76:77], v[202:203]
	v_pk_fma_f32 v[204:205], v[188:189], v[78:79], v[204:205]
	v_pk_fma_f32 v[206:207], v[190:191], v[80:81], v[206:207]
	v_pk_fma_f32 v[208:209], v[192:193], v[82:83], v[208:209]
	v_mul_f32_e32 v210, 0xbfb8aa3b, v202
	v_mul_f32_e32 v211, 0xbfb8aa3b, v203
	v_mul_f32_e32 v212, 0xbfb8aa3b, v204
	v_mul_f32_e32 v213, 0xbfb8aa3b, v205
	v_mul_f32_e32 v214, 0xbfb8aa3b, v206
	v_mul_f32_e32 v215, 0xbfb8aa3b, v207
	v_mul_f32_e32 v216, 0xbfb8aa3b, v208
	v_mul_f32_e32 v217, 0xbfb8aa3b, v209
	v_exp_f32_e32 v210, v210
	v_exp_f32_e32 v211, v211
	v_exp_f32_e32 v212, v212
	v_exp_f32_e32 v213, v213
	v_exp_f32_e32 v214, v214
	v_exp_f32_e32 v215, v215
	v_exp_f32_e32 v216, v216
	v_exp_f32_e32 v217, v217
	v_add_f32_e32 v210, 1.0, v210
	v_add_f32_e32 v211, 1.0, v211
	v_add_f32_e32 v212, 1.0, v212
	v_add_f32_e32 v213, 1.0, v213
	v_add_f32_e32 v214, 1.0, v214
	v_add_f32_e32 v215, 1.0, v215
	v_add_f32_e32 v216, 1.0, v216
	v_add_f32_e32 v217, 1.0, v217
	v_rcp_f32_e32 v210, v210
	v_rcp_f32_e32 v211, v211
	v_rcp_f32_e32 v212, v212
	v_rcp_f32_e32 v213, v213
	v_rcp_f32_e32 v214, v214
	v_rcp_f32_e32 v215, v215
	v_rcp_f32_e32 v216, v216
	v_rcp_f32_e32 v217, v217
	v_pk_mul_f32 v[202:203], v[202:203], v[210:211]
	v_pk_mul_f32 v[204:205], v[204:205], v[212:213]
	v_pk_mul_f32 v[206:207], v[206:207], v[214:215]
	v_pk_mul_f32 v[208:209], v[208:209], v[216:217]
	v_cvt_pk_bf16_f32 v222, v202, v203
	v_cvt_pk_bf16_f32 v223, v204, v205
	v_cvt_pk_bf16_f32 v224, v206, v207
	v_cvt_pk_bf16_f32 v225, v208, v209
	global_store_dwordx4 v238, v[222:225], s[24:25] offset:1024
	v_pk_fma_f32 v[202:203], v[162:163], v[60:61], v[194:195]
	v_pk_fma_f32 v[204:205], v[164:165], v[62:63], v[196:197]
	v_pk_fma_f32 v[206:207], v[166:167], v[64:65], v[198:199]
; __device__ __forceinline__ unsigned cvt_pk(float lo, float hi) { f32x2 v = {lo, hi}; bf16x2_t b = __builtin_convertvector(v, bf16x2_t); return __builtin_bit_cast(unsigned, b); }
; __device__ __forceinline__ float bflo(unsigned w) { return __uint_as_float(w << 16); }
; __device__ __forceinline__ float bfhi(unsigned w) { return __uint_as_float(w & 0xffff0000u); }
; __device__ __forceinline__ float silu_f(float x) { return x * __builtin_amdgcn_rcpf(1.f + __builtin_amdgcn_exp2f(-1.4426950409f * x)); }
; __device__ __forceinline__ void ssd_prompt_item(const Params& p, int item, const int wv) {
;     ...
; #pragma unroll
;       for (int jj = 0; jj < 8; ++jj) {
;         float o[8];
; #pragma unroll
;         for (int e = 0; e < 8; ++e) o[e] = bias[e];
; #pragma unroll
;         for (int k = 0; k < 4; ++k) {
;           u32x4 uu = u[jj + k];
;           o[0] += w[k][0] * bflo(uu.x); o[1] += w[k][1] * bfhi(uu.x); o[2] += w[k][2] * bflo(uu.y); o[3] += w[k][3] * bfhi(uu.y);
;           o[4] += w[k][4] * bflo(uu.z); o[5] += w[k][5] * bfhi(uu.z); o[6] += w[k][6] * bflo(uu.w); o[7] += w[k][7] * bfhi(uu.w);
;         }
; #pragma unroll
;         for (int e = 0; e < 8; ++e) o[e] = silu_f(o[e]);
; #pragma unroll
;         for (int e2 = 0; e2 < 4; ++e2) outp[jj][e2] = cvt_pk(o[2 * e2], o[2 * e2 + 1]);
;       }
	v_pk_fma_f32 v[208:209], v[168:169], v[66:67], v[200:201]
	v_pk_fma_f32 v[202:203], v[170:171], v[68:69], v[202:203]
	v_pk_fma_f32 v[204:205], v[172:173], v[70:71], v[204:205]
	v_pk_fma_f32 v[206:207], v[174:175], v[72:73], v[206:207]
	v_pk_fma_f32 v[208:209], v[176:177], v[74:75], v[208:209]
	v_pk_fma_f32 v[202:203], v[178:179], v[76:77], v[202:203]
	v_pk_fma_f32 v[204:205], v[180:181], v[78:79], v[204:205]
	v_pk_fma_f32 v[206:207], v[182:183], v[80:81], v[206:207]
	v_pk_fma_f32 v[208:209], v[184:185], v[82:83], v[208:209]
	v_pk_fma_f32 v[202:203], v[186:187], v[84:85], v[202:203]
	v_pk_fma_f32 v[204:205], v[188:189], v[86:87], v[204:205]
	v_pk_fma_f32 v[206:207], v[190:191], v[88:89], v[206:207]
	v_pk_fma_f32 v[208:209], v[192:193], v[90:91], v[208:209]
	v_mul_f32_e32 v210, 0xbfb8aa3b, v202
	v_mul_f32_e32 v211, 0xbfb8aa3b, v203
	v_mul_f32_e32 v212, 0xbfb8aa3b, v204
	v_mul_f32_e32 v213, 0xbfb8aa3b, v205
	v_mul_f32_e32 v214, 0xbfb8aa3b, v206
	v_mul_f32_e32 v215, 0xbfb8aa3b, v207
	v_mul_f32_e32 v216, 0xbfb8aa3b, v208
	v_mul_f32_e32 v217, 0xbfb8aa3b, v209
	v_exp_f32_e32 v210, v210
	v_exp_f32_e32 v211, v211
	v_exp_f32_e32 v212, v212
	v_exp_f32_e32 v213, v213
	v_exp_f32_e32 v214, v214
	v_exp_f32_e32 v215, v215
	v_exp_f32_e32 v216, v216
	v_exp_f32_e32 v217, v217
	v_add_f32_e32 v210, 1.0, v210
	v_add_f32_e32 v211, 1.0, v211
	v_add_f32_e32 v212, 1.0, v212
	v_add_f32_e32 v213, 1.0, v213
	v_add_f32_e32 v214, 1.0, v214
	v_add_f32_e32 v215, 1.0, v215
	v_add_f32_e32 v216, 1.0, v216
	v_add_f32_e32 v217, 1.0, v217
	v_rcp_f32_e32 v210, v210
	v_rcp_f32_e32 v211, v211
	v_rcp_f32_e32 v212, v212
	v_rcp_f32_e32 v213, v213
	v_rcp_f32_e32 v214, v214
	v_rcp_f32_e32 v215, v215
	v_rcp_f32_e32 v216, v216
	v_rcp_f32_e32 v217, v217
	v_pk_mul_f32 v[202:203], v[202:203], v[210:211]
	v_pk_mul_f32 v[204:205], v[204:205], v[212:213]
	v_pk_mul_f32 v[206:207], v[206:207], v[214:215]
	v_pk_mul_f32 v[208:209], v[208:209], v[216:217]
	v_cvt_pk_bf16_f32 v218, v202, v203
	v_cvt_pk_bf16_f32 v219, v204, v205
	v_cvt_pk_bf16_f32 v220, v206, v207
	v_cvt_pk_bf16_f32 v221, v208, v209
	global_store_dwordx4 v238, v[218:221], s[24:25] offset:2048
	v_pk_fma_f32 v[202:203], v[162:163], v[68:69], v[194:195]
	v_pk_fma_f32 v[204:205], v[164:165], v[70:71], v[196:197]
	v_pk_fma_f32 v[206:207], v[166:167], v[72:73], v[198:199]
	v_pk_fma_f32 v[208:209], v[168:169], v[74:75], v[200:201]
	v_pk_fma_f32 v[202:203], v[170:171], v[76:77], v[202:203]
	v_pk_fma_f32 v[204:205], v[172:173], v[78:79], v[204:205]
	v_pk_fma_f32 v[206:207], v[174:175], v[80:81], v[206:207]
	v_pk_fma_f32 v[208:209], v[176:177], v[82:83], v[208:209]
	v_pk_fma_f32 v[202:203], v[178:179], v[84:85], v[202:203]
	v_pk_fma_f32 v[204:205], v[180:181], v[86:87], v[204:205]
	v_pk_fma_f32 v[206:207], v[182:183], v[88:89], v[206:207]
	v_pk_fma_f32 v[208:209], v[184:185], v[90:91], v[208:209]
	v_pk_fma_f32 v[202:203], v[186:187], v[92:93], v[202:203]
	v_pk_fma_f32 v[204:205], v[188:189], v[94:95], v[204:205]
	v_pk_fma_f32 v[206:207], v[190:191], v[96:97], v[206:207]
	v_pk_fma_f32 v[208:209], v[192:193], v[98:99], v[208:209]
	v_mul_f32_e32 v210, 0xbfb8aa3b, v202
	v_mul_f32_e32 v211, 0xbfb8aa3b, v203
	v_mul_f32_e32 v212, 0xbfb8aa3b, v204
	v_mul_f32_e32 v213, 0xbfb8aa3b, v205
	v_mul_f32_e32 v214, 0xbfb8aa3b, v206
	v_mul_f32_e32 v215, 0xbfb8aa3b, v207
	v_mul_f32_e32 v216, 0xbfb8aa3b, v208
	v_mul_f32_e32 v217, 0xbfb8aa3b, v209
	v_exp_f32_e32 v210, v210
	v_exp_f32_e32 v211, v211
	v_exp_f32_e32 v212, v212
	v_exp_f32_e32 v213, v213
	v_exp_f32_e32 v214, v214
	v_exp_f32_e32 v215, v215
	v_exp_f32_e32 v216, v216
	v_exp_f32_e32 v217, v217
	v_add_f32_e32 v210, 1.0, v210
	v_add_f32_e32 v211, 1.0, v211
	v_add_f32_e32 v212, 1.0, v212
	v_add_f32_e32 v213, 1.0, v213
	v_add_f32_e32 v214, 1.0, v214
	v_add_f32_e32 v215, 1.0, v215
	v_add_f32_e32 v216, 1.0, v216
	v_add_f32_e32 v217, 1.0, v217
	v_rcp_f32_e32 v210, v210
	v_rcp_f32_e32 v211, v211
	v_rcp_f32_e32 v212, v212
	v_rcp_f32_e32 v213, v213
	v_rcp_f32_e32 v214, v214
	v_rcp_f32_e32 v215, v215
	v_rcp_f32_e32 v216, v216
	v_rcp_f32_e32 v217, v217
	v_pk_mul_f32 v[202:203], v[202:203], v[210:211]
	v_pk_mul_f32 v[204:205], v[204:205], v[212:213]
	v_pk_mul_f32 v[206:207], v[206:207], v[214:215]
	v_pk_mul_f32 v[208:209], v[208:209], v[216:217]
	v_cvt_pk_bf16_f32 v222, v202, v203
	v_cvt_pk_bf16_f32 v223, v204, v205
	v_cvt_pk_bf16_f32 v224, v206, v207
	v_cvt_pk_bf16_f32 v225, v208, v209
	global_store_dwordx4 v238, v[222:225], s[24:25] offset:3072
	v_pk_fma_f32 v[202:203], v[162:163], v[76:77], v[194:195]
	v_pk_fma_f32 v[204:205], v[164:165], v[78:79], v[196:197]
	v_pk_fma_f32 v[206:207], v[166:167], v[80:81], v[198:199]
	v_pk_fma_f32 v[208:209], v[168:169], v[82:83], v[200:201]
	v_pk_fma_f32 v[202:203], v[170:171], v[84:85], v[202:203]
	v_pk_fma_f32 v[204:205], v[172:173], v[86:87], v[204:205]
	v_pk_fma_f32 v[206:207], v[174:175], v[88:89], v[206:207]
	v_pk_fma_f32 v[208:209], v[176:177], v[90:91], v[208:209]
	v_pk_fma_f32 v[202:203], v[178:179], v[92:93], v[202:203]
	v_pk_fma_f32 v[204:205], v[180:181], v[94:95], v[204:205]
	v_pk_fma_f32 v[206:207], v[182:183], v[96:97], v[206:207]
	v_pk_fma_f32 v[208:209], v[184:185], v[98:99], v[208:209]
	v_pk_fma_f32 v[202:203], v[186:187], v[100:101], v[202:203]
	v_pk_fma_f32 v[204:205], v[188:189], v[102:103], v[204:205]
	v_pk_fma_f32 v[206:207], v[190:191], v[104:105], v[206:207]
	v_pk_fma_f32 v[208:209], v[192:193], v[106:107], v[208:209]
	v_mul_f32_e32 v210, 0xbfb8aa3b, v202
	v_mul_f32_e32 v211, 0xbfb8aa3b, v203
	v_mul_f32_e32 v212, 0xbfb8aa3b, v204
	v_mul_f32_e32 v213, 0xbfb8aa3b, v205
	v_mul_f32_e32 v214, 0xbfb8aa3b, v206
	v_mul_f32_e32 v215, 0xbfb8aa3b, v207
; __device__ __forceinline__ unsigned cvt_pk(float lo, float hi) { f32x2 v = {lo, hi}; bf16x2_t b = __builtin_convertvector(v, bf16x2_t); return __builtin_bit_cast(unsigned, b); }
; __device__ __forceinline__ float bflo(unsigned w) { return __uint_as_float(w << 16); }
; __device__ __forceinline__ float bfhi(unsigned w) { return __uint_as_float(w & 0xffff0000u); }
; __device__ __forceinline__ float silu_f(float x) { return x * __builtin_amdgcn_rcpf(1.f + __builtin_amdgcn_exp2f(-1.4426950409f * x)); }
; __device__ __forceinline__ void ssd_prompt_item(const Params& p, int item, const int wv) {
;     ...
; #pragma unroll
;       for (int jj = 0; jj < 8; ++jj) {
;         float o[8];
; #pragma unroll
;         for (int e = 0; e < 8; ++e) o[e] = bias[e];
; #pragma unroll
;         for (int k = 0; k < 4; ++k) {
;           u32x4 uu = u[jj + k];
;           o[0] += w[k][0] * bflo(uu.x); o[1] += w[k][1] * bfhi(uu.x); o[2] += w[k][2] * bflo(uu.y); o[3] += w[k][3] * bfhi(uu.y);
;           o[4] += w[k][4] * bflo(uu.z); o[5] += w[k][5] * bfhi(uu.z); o[6] += w[k][6] * bflo(uu.w); o[7] += w[k][7] * bfhi(uu.w);
;         }
; #pragma unroll
;         for (int e = 0; e < 8; ++e) o[e] = silu_f(o[e]);
; #pragma unroll
;         for (int e2 = 0; e2 < 4; ++e2) outp[jj][e2] = cvt_pk(o[2 * e2], o[2 * e2 + 1]);
;       }
	v_mul_f32_e32 v216, 0xbfb8aa3b, v208
	v_mul_f32_e32 v217, 0xbfb8aa3b, v209
	v_exp_f32_e32 v210, v210
	v_exp_f32_e32 v211, v211
	v_exp_f32_e32 v212, v212
	v_exp_f32_e32 v213, v213
	v_exp_f32_e32 v214, v214
	v_exp_f32_e32 v215, v215
	v_exp_f32_e32 v216, v216
	v_exp_f32_e32 v217, v217
	v_add_f32_e32 v210, 1.0, v210
	v_add_f32_e32 v211, 1.0, v211
	v_add_f32_e32 v212, 1.0, v212
	v_add_f32_e32 v213, 1.0, v213
	v_add_f32_e32 v214, 1.0, v214
	v_add_f32_e32 v215, 1.0, v215
	v_add_f32_e32 v216, 1.0, v216
	v_add_f32_e32 v217, 1.0, v217
	v_rcp_f32_e32 v210, v210
	v_rcp_f32_e32 v211, v211
	v_rcp_f32_e32 v212, v212
	v_rcp_f32_e32 v213, v213
	v_rcp_f32_e32 v214, v214
	v_rcp_f32_e32 v215, v215
	v_rcp_f32_e32 v216, v216
	v_rcp_f32_e32 v217, v217
	v_pk_mul_f32 v[202:203], v[202:203], v[210:211]
	v_pk_mul_f32 v[204:205], v[204:205], v[212:213]
	v_pk_mul_f32 v[206:207], v[206:207], v[214:215]
	v_pk_mul_f32 v[208:209], v[208:209], v[216:217]
	v_cvt_pk_bf16_f32 v218, v202, v203
	v_cvt_pk_bf16_f32 v219, v204, v205
	v_cvt_pk_bf16_f32 v220, v206, v207
	v_cvt_pk_bf16_f32 v221, v208, v209
	global_store_dwordx4 v239, v[218:221], s[24:25]
	v_pk_fma_f32 v[202:203], v[162:163], v[84:85], v[194:195]
	v_pk_fma_f32 v[204:205], v[164:165], v[86:87], v[196:197]
	v_pk_fma_f32 v[206:207], v[166:167], v[88:89], v[198:199]
	v_pk_fma_f32 v[208:209], v[168:169], v[90:91], v[200:201]
	v_pk_fma_f32 v[202:203], v[170:171], v[92:93], v[202:203]
	v_pk_fma_f32 v[204:205], v[172:173], v[94:95], v[204:205]
	v_pk_fma_f32 v[206:207], v[174:175], v[96:97], v[206:207]
	v_pk_fma_f32 v[208:209], v[176:177], v[98:99], v[208:209]
	v_pk_fma_f32 v[202:203], v[178:179], v[100:101], v[202:203]
	v_pk_fma_f32 v[204:205], v[180:181], v[102:103], v[204:205]
	v_pk_fma_f32 v[206:207], v[182:183], v[104:105], v[206:207]
	v_pk_fma_f32 v[208:209], v[184:185], v[106:107], v[208:209]
	v_pk_fma_f32 v[202:203], v[186:187], v[108:109], v[202:203]
	v_pk_fma_f32 v[204:205], v[188:189], v[110:111], v[204:205]
	v_pk_fma_f32 v[206:207], v[190:191], v[112:113], v[206:207]
	v_pk_fma_f32 v[208:209], v[192:193], v[114:115], v[208:209]
	v_mul_f32_e32 v210, 0xbfb8aa3b, v202
	v_mul_f32_e32 v211, 0xbfb8aa3b, v203
	v_mul_f32_e32 v212, 0xbfb8aa3b, v204
	v_mul_f32_e32 v213, 0xbfb8aa3b, v205
	v_mul_f32_e32 v214, 0xbfb8aa3b, v206
	v_mul_f32_e32 v215, 0xbfb8aa3b, v207
	v_mul_f32_e32 v216, 0xbfb8aa3b, v208
	v_mul_f32_e32 v217, 0xbfb8aa3b, v209
	v_exp_f32_e32 v210, v210
	v_exp_f32_e32 v211, v211
	v_exp_f32_e32 v212, v212
	v_exp_f32_e32 v213, v213
	v_exp_f32_e32 v214, v214
	v_exp_f32_e32 v215, v215
	v_exp_f32_e32 v216, v216
	v_exp_f32_e32 v217, v217
	v_add_f32_e32 v210, 1.0, v210
	v_add_f32_e32 v211, 1.0, v211
	v_add_f32_e32 v212, 1.0, v212
	v_add_f32_e32 v213, 1.0, v213
	v_add_f32_e32 v214, 1.0, v214
	v_add_f32_e32 v215, 1.0, v215
	v_add_f32_e32 v216, 1.0, v216
	v_add_f32_e32 v217, 1.0, v217
	v_rcp_f32_e32 v210, v210
	v_rcp_f32_e32 v211, v211
	v_rcp_f32_e32 v212, v212
	v_rcp_f32_e32 v213, v213
	v_rcp_f32_e32 v214, v214
	v_rcp_f32_e32 v215, v215
	v_rcp_f32_e32 v216, v216
	v_rcp_f32_e32 v217, v217
	v_pk_mul_f32 v[202:203], v[202:203], v[210:211]
	v_pk_mul_f32 v[204:205], v[204:205], v[212:213]
	v_pk_mul_f32 v[206:207], v[206:207], v[214:215]
	v_pk_mul_f32 v[208:209], v[208:209], v[216:217]
	v_cvt_pk_bf16_f32 v222, v202, v203
	v_cvt_pk_bf16_f32 v223, v204, v205
	v_cvt_pk_bf16_f32 v224, v206, v207
	v_cvt_pk_bf16_f32 v225, v208, v209
	global_store_dwordx4 v239, v[222:225], s[24:25] offset:1024
	v_pk_fma_f32 v[202:203], v[162:163], v[92:93], v[194:195]
	v_pk_fma_f32 v[204:205], v[164:165], v[94:95], v[196:197]
	v_pk_fma_f32 v[206:207], v[166:167], v[96:97], v[198:199]
	v_pk_fma_f32 v[208:209], v[168:169], v[98:99], v[200:201]
	v_pk_fma_f32 v[202:203], v[170:171], v[100:101], v[202:203]
	v_pk_fma_f32 v[204:205], v[172:173], v[102:103], v[204:205]
	v_pk_fma_f32 v[206:207], v[174:175], v[104:105], v[206:207]
	v_pk_fma_f32 v[208:209], v[176:177], v[106:107], v[208:209]
	v_pk_fma_f32 v[202:203], v[178:179], v[108:109], v[202:203]
	v_pk_fma_f32 v[204:205], v[180:181], v[110:111], v[204:205]
	v_pk_fma_f32 v[206:207], v[182:183], v[112:113], v[206:207]
	v_pk_fma_f32 v[208:209], v[184:185], v[114:115], v[208:209]
	v_pk_fma_f32 v[202:203], v[186:187], v[116:117], v[202:203]
	v_pk_fma_f32 v[204:205], v[188:189], v[118:119], v[204:205]
	v_pk_fma_f32 v[206:207], v[190:191], v[120:121], v[206:207]
	v_pk_fma_f32 v[208:209], v[192:193], v[122:123], v[208:209]
	v_mul_f32_e32 v210, 0xbfb8aa3b, v202
	v_mul_f32_e32 v211, 0xbfb8aa3b, v203
	v_mul_f32_e32 v212, 0xbfb8aa3b, v204
	v_mul_f32_e32 v213, 0xbfb8aa3b, v205
	v_mul_f32_e32 v214, 0xbfb8aa3b, v206
	v_mul_f32_e32 v215, 0xbfb8aa3b, v207
	v_mul_f32_e32 v216, 0xbfb8aa3b, v208
	v_mul_f32_e32 v217, 0xbfb8aa3b, v209
	v_exp_f32_e32 v210, v210
	v_exp_f32_e32 v211, v211
	v_exp_f32_e32 v212, v212
	v_exp_f32_e32 v213, v213
	v_exp_f32_e32 v214, v214
	v_exp_f32_e32 v215, v215
	v_exp_f32_e32 v216, v216
	v_exp_f32_e32 v217, v217
	v_add_f32_e32 v210, 1.0, v210
	v_add_f32_e32 v211, 1.0, v211
	v_add_f32_e32 v212, 1.0, v212
	v_add_f32_e32 v213, 1.0, v213
	v_add_f32_e32 v214, 1.0, v214
	v_add_f32_e32 v215, 1.0, v215
	v_add_f32_e32 v216, 1.0, v216
	v_add_f32_e32 v217, 1.0, v217
	v_rcp_f32_e32 v210, v210
	v_rcp_f32_e32 v211, v211
	v_rcp_f32_e32 v212, v212
	v_rcp_f32_e32 v213, v213
	v_rcp_f32_e32 v214, v214
	v_rcp_f32_e32 v215, v215
	v_rcp_f32_e32 v216, v216
	v_rcp_f32_e32 v217, v217
	v_pk_mul_f32 v[202:203], v[202:203], v[210:211]
	v_pk_mul_f32 v[204:205], v[204:205], v[212:213]
	v_pk_mul_f32 v[206:207], v[206:207], v[214:215]
	v_pk_mul_f32 v[208:209], v[208:209], v[216:217]
	v_cvt_pk_bf16_f32 v218, v202, v203
; __device__ __forceinline__ unsigned cvt_pk(float lo, float hi) { f32x2 v = {lo, hi}; bf16x2_t b = __builtin_convertvector(v, bf16x2_t); return __builtin_bit_cast(unsigned, b); }
; __device__ __forceinline__ float bflo(unsigned w) { return __uint_as_float(w << 16); }
; __device__ __forceinline__ void ssd_prompt_item(const Params& p, int item, const int wv) {
;   const int lane = lane_fresh(), wid = wv, tid = wv * 64 + lane, fr = lane & 15, fq = lane >> 4;
;   const int h = item & 15, b = item >> 4, g = h >> 3;
;   char* ws = p.ws;
;   u16* C_l = (u16*)g_shm;
;   u16* B_l = C_l + 128 * 136;
;   u16* G_l = B_l;
;   u16* BT_l = B_l + 128 * 136;
;   u16* xT_l = BT_l + 128 * 136;
;   u16* xw_l = xT_l + 64 * 136;
;   u16* h_l = xw_l + 64 * 136;
;   float* acum_l = (float*)(h_l + 64 * 136);
;   float* dt_l = acum_l + 128;
;   const u16* XBC = (const u16*)(ws + OFF_XBC);
;   const u16* ZS = (const u16*)(ws + OFF_ZS);
;   const float* DT = (const float*)(ws + OFF_DT);
;   u16* Y = (u16*)((char*)p.out + OOFF_XN);
;   float* YPS = (float*)(ws + OFF_YPS);
;   const float Ah = -__expf(p.in[16][h]);
;   const float Dh = p.in[17][h];
;   const float* convw = p.in[13];
;   const float* convb = p.in[14];
;   const int cc = tid & 31, rg = tid >> 5;
;   const int colbc = (cc < 16) ? (1024 + g * 128 + cc * 8) : (1280 + g * 128 + (cc - 16) * 8);
;   const int xc = tid & 7, xr = tid >> 3;
;   const int colx = h * 64 + xc * 8;
;   const int j0 = rg * 8;
;   f32x4 hacc[4];
; #pragma unroll
;   for (int pb = 0; pb < 4; ++pb) hacc[pb] = (f32x4){0.f, 0.f, 0.f, 0.f};
;   u32x4 u[11], ux[5];
;   float a0 = 0.f, a1 = 0.f;
;     ...
;   SSD_PREFETCH(0);
;     ...
; #pragma unroll
;       for (int jj = 0; jj < 8; ++jj) {
;         float o[8];
; #pragma unroll
;         for (int e = 0; e < 8; ++e) o[e] = bias[e];
; #pragma unroll
;         for (int k = 0; k < 4; ++k) {
;           u32x4 uu = u[jj + k];
;           o[0] += w[k][0] * bflo(uu.x); o[1] += w[k][1] * bfhi(uu.x); o[2] += w[k][2] * bflo(uu.y); o[3] += w[k][3] * bfhi(uu.y);
;           o[4] += w[k][4] * bflo(uu.z); o[5] += w[k][5] * bfhi(uu.z); o[6] += w[k][6] * bflo(uu.w); o[7] += w[k][7] * bfhi(uu.w);
;         }
; #pragma unroll
;         for (int e = 0; e < 8; ++e) o[e] = silu_f(o[e]);
; #pragma unroll
;         for (int e2 = 0; e2 < 4; ++e2) outp[jj][e2] = cvt_pk(o[2 * e2], o[2 * e2 + 1]);
;       }
	v_cvt_pk_bf16_f32 v219, v204, v205
	v_cvt_pk_bf16_f32 v220, v206, v207
	v_cvt_pk_bf16_f32 v221, v208, v209
	global_store_dwordx4 v239, v[218:221], s[24:25] offset:2048
	v_pk_fma_f32 v[202:203], v[162:163], v[100:101], v[194:195]
	v_pk_fma_f32 v[204:205], v[164:165], v[102:103], v[196:197]
	v_pk_fma_f32 v[206:207], v[166:167], v[104:105], v[198:199]
	v_pk_fma_f32 v[208:209], v[168:169], v[106:107], v[200:201]
	v_pk_fma_f32 v[202:203], v[170:171], v[108:109], v[202:203]
	v_pk_fma_f32 v[204:205], v[172:173], v[110:111], v[204:205]
	v_pk_fma_f32 v[206:207], v[174:175], v[112:113], v[206:207]
	v_pk_fma_f32 v[208:209], v[176:177], v[114:115], v[208:209]
	v_pk_fma_f32 v[202:203], v[178:179], v[116:117], v[202:203]
	v_pk_fma_f32 v[204:205], v[180:181], v[118:119], v[204:205]
	v_pk_fma_f32 v[206:207], v[182:183], v[120:121], v[206:207]
	v_pk_fma_f32 v[208:209], v[184:185], v[122:123], v[208:209]
	v_pk_fma_f32 v[202:203], v[186:187], v[124:125], v[202:203]
	v_pk_fma_f32 v[204:205], v[188:189], v[126:127], v[204:205]
	v_pk_fma_f32 v[206:207], v[190:191], v[128:129], v[206:207]
	v_pk_fma_f32 v[208:209], v[192:193], v[130:131], v[208:209]
	v_mul_f32_e32 v210, 0xbfb8aa3b, v202
	v_mul_f32_e32 v211, 0xbfb8aa3b, v203
	v_mul_f32_e32 v212, 0xbfb8aa3b, v204
	v_mul_f32_e32 v213, 0xbfb8aa3b, v205
	v_mul_f32_e32 v214, 0xbfb8aa3b, v206
	v_mul_f32_e32 v215, 0xbfb8aa3b, v207
	v_mul_f32_e32 v216, 0xbfb8aa3b, v208
	v_mul_f32_e32 v217, 0xbfb8aa3b, v209
	v_exp_f32_e32 v210, v210
	v_exp_f32_e32 v211, v211
	v_exp_f32_e32 v212, v212
	v_exp_f32_e32 v213, v213
	v_exp_f32_e32 v214, v214
	v_exp_f32_e32 v215, v215
	v_exp_f32_e32 v216, v216
	v_exp_f32_e32 v217, v217
	v_add_f32_e32 v210, 1.0, v210
	v_add_f32_e32 v211, 1.0, v211
	v_add_f32_e32 v212, 1.0, v212
	v_add_f32_e32 v213, 1.0, v213
	v_add_f32_e32 v214, 1.0, v214
	v_add_f32_e32 v215, 1.0, v215
	v_add_f32_e32 v216, 1.0, v216
	v_add_f32_e32 v217, 1.0, v217
	v_rcp_f32_e32 v210, v210
	v_rcp_f32_e32 v211, v211
	v_rcp_f32_e32 v212, v212
	v_rcp_f32_e32 v213, v213
	v_rcp_f32_e32 v214, v214
	v_rcp_f32_e32 v215, v215
	v_rcp_f32_e32 v216, v216
	v_rcp_f32_e32 v217, v217
	v_pk_mul_f32 v[202:203], v[202:203], v[210:211]
	v_pk_mul_f32 v[204:205], v[204:205], v[212:213]
	v_pk_mul_f32 v[206:207], v[206:207], v[214:215]
	v_pk_mul_f32 v[208:209], v[208:209], v[216:217]
	v_cvt_pk_bf16_f32 v222, v202, v203
	v_cvt_pk_bf16_f32 v223, v204, v205
	v_cvt_pk_bf16_f32 v224, v206, v207
	v_cvt_pk_bf16_f32 v225, v208, v209
	global_store_dwordx4 v239, v[222:225], s[24:25] offset:3072
	s_add_u32 s5, s5, 1
	s_cmp_lt_u32 s5, s6
	s_cbranch_scc1 .Lssdp_unit
	s_waitcnt vmcnt(0)
	s_barrier
	s_cmp_lg_u32 s82, 0
	s_cbranch_scc1 .Lssdp_wait_done
	s_mov_b64 exec, 1
	buffer_wbl2 sc1
	s_waitcnt vmcnt(0)
	s_lshl_b32 s20, s0, 1
	s_add_u32 s20, s20, s4
	s_lshl_b32 s20, s20, 6
	s_add_u32 s20, s20, 0x1241d000
	s_add_u32 s58, s50, s20
	s_addc_u32 s59, s51, 0
	v_mov_b32_e32 v230, 0
	v_mov_b32_e32 v231, 1
	global_atomic_add v230, v231, s[58:59]
	s_waitcnt vmcnt(0)
	s_mov_b32 s60, 0
.Lssdp_spin:
	global_load_dword v231, v230, s[58:59] sc1
	s_waitcnt vmcnt(0)
	v_readfirstlane_b32 s61, v231
	s_cmp_ge_u32 s61, 8
	s_cbranch_scc1 .Lssdp_spin_done
	s_sleep 1
	s_add_u32 s60, s60, 1
	s_cmp_lt_u32 s60, 0x400000
	s_cbranch_scc1 .Lssdp_spin
.Lssdp_spin_done:
	s_mov_b64 exec, -1
.Lssdp_wait_done:
	s_barrier
	buffer_inv sc1
	s_waitcnt vmcnt(0)
	s_and_b32 s6, s68, 15
	v_readlane_b32 s52, v251, 22
	s_lshl_b32 s18, s6, 2
	v_readlane_b32 s53, v251, 23
	v_mbcnt_lo_u32_b32 v71, -1, 0
	v_mbcnt_hi_u32_b32 v71, -1, v71
	v_mov_b32_e32 v0, s18
	v_readlane_b32 s54, v251, 24
	v_readlane_b32 s55, v251, 25
	s_mov_b64 s[8:9], s[52:53]
	v_and_b32_e32 v72, 31, v71
	s_lshl_b32 s0, s68, 4
	s_mov_b64 s[10:11], s[54:55]
	global_load_dword v69, v0, s[8:9]
	global_load_dword v144, v0, s[10:11]
	s_and_b32 s0, s0, 0x80
	v_lshlrev_b32_e32 v0, 3, v72
	s_waitcnt lgkmcnt(0)
	v_or_b32_e32 v1, s0, v0
	s_addk_i32 s0, 0x480
	v_or_b32_e32 v1, 0x400, v1
	v_add_u32_e32 v0, s0, v0
	v_cmp_gt_u32_e32 vcc, 16, v72
	v_lshlrev_b32_e32 v65, 3, v71
	v_add_u32_e32 v64, s82, v71
	v_cndmask_b32_e32 v75, v0, v1, vcc
	v_and_b32_e32 v67, 56, v65
	v_readlane_b32 s8, v250, 8
	v_ashrrev_i32_e32 v70, 3, v64
	v_ashrrev_i32_e32 v40, 2, v64
	v_lshlrev_b32_e32 v142, 1, v75
	v_readlane_b32 s9, v250, 9
	v_lshl_or_b32 v76, s6, 6, v67
	v_and_b32_e32 v66, -8, v40
	v_lshl_add_u64 v[146:147], s[8:9], 0, v[142:143]
	v_lshlrev_b32_e32 v68, 1, v70
	v_lshlrev_b32_e32 v142, 1, v76
	s_lshl_b32 s0, s68, 7
	v_add_u32_e32 v0, -3, v66
	v_cmp_lt_i32_e64 s[12:13], 7, v40
	v_add_u32_e32 v2, -2, v66
	v_add_u32_e32 v8, -1, v66
	v_cmp_lt_i32_e64 s[4:5], -1, v40
	v_or_b32_e32 v16, 1, v66
	v_or_b32_e32 v18, 2, v66
	v_or_b32_e32 v24, 3, v66
	v_or_b32_e32 v26, 4, v66
	v_or_b32_e32 v32, 5, v66
	v_or_b32_e32 v34, 6, v66
	v_or_b32_e32 v74, 7, v40
	v_add_u32_e32 v42, -3, v68
	v_lshl_add_u64 v[56:57], s[8:9], 0, v[142:143]
	v_cmp_lt_i32_e64 s[10:11], 1, v70
	v_add_u32_e32 v48, -2, v68
	v_cmp_lt_i32_e64 s[8:9], 0, v70
	v_add_u32_e32 v50, -1, v68
	v_cmp_lt_i32_e64 s[6:7], -1, v70
	v_or_b32_e32 v60, 1, v68
	s_and_b32 s41, s0, 0x3800
	v_cndmask_b32_e64 v0, 0, v0, s[12:13]
	v_cndmask_b32_e64 v2, 0, v2, s[12:13]
	v_cndmask_b32_e64 v8, 0, v8, s[12:13]
	v_cndmask_b32_e64 v10, 0, v66, s[4:5]
	v_cndmask_b32_e64 v16, 0, v16, s[4:5]
	v_cndmask_b32_e64 v18, 0, v18, s[4:5]
	v_cndmask_b32_e64 v24, 0, v24, s[4:5]
	v_cndmask_b32_e64 v26, 0, v26, s[4:5]
	v_cndmask_b32_e64 v32, 0, v32, s[4:5]
	v_cndmask_b32_e64 v34, 0, v34, s[4:5]
	v_cndmask_b32_e64 v40, 0, v74, s[4:5]
	v_cndmask_b32_e64 v42, 0, v42, s[10:11]
	v_cndmask_b32_e64 v48, 0, v48, s[8:9]
	v_cndmask_b32_e64 v50, 0, v50, s[8:9]
; __device__ __forceinline__ void ssd_prompt_item(const Params& p, int item, const int wv) {
;     ...
;   SSD_PREFETCH(0);
; #pragma unroll 1
	v_cndmask_b32_e64 v58, 0, v68, s[6:7]
	v_cndmask_b32_e64 v60, 0, v60, s[6:7]
	v_add_u32_e32 v0, s41, v0
	v_add_u32_e32 v2, s41, v2
	v_add_u32_e32 v8, s41, v8
	v_add_u32_e32 v10, s41, v10
	v_add_u32_e32 v16, s41, v16
	v_add_u32_e32 v18, s41, v18
	v_add_u32_e32 v24, s41, v24
	v_add_u32_e32 v26, s41, v26
	v_add_u32_e32 v32, s41, v32
	v_add_u32_e32 v34, s41, v34
	v_add_u32_e32 v40, s41, v40
	v_add_u32_e32 v42, s41, v42
	v_add_u32_e32 v48, s41, v48
	v_add_u32_e32 v50, s41, v50
	v_add_u32_e32 v58, s41, v58
	v_add_u32_e32 v60, s41, v60
	v_mad_i64_i32 v[44:45], s[0:1], v42, s33, v[56:57]
	v_mad_i64_i32 v[48:49], s[0:1], v48, s33, v[56:57]
	v_mad_i64_i32 v[52:53], s[0:1], v50, s33, v[56:57]
	v_mad_i64_i32 v[58:59], s[0:1], v58, s33, v[56:57]
	v_mad_i64_i32 v[60:61], s[0:1], v60, s33, v[56:57]
	s_nop 0
	s_nop 0
	s_nop 0
	s_nop 0
	s_nop 0
	s_nop 0
	s_nop 0
	s_nop 0
	s_nop 0
	s_nop 0
	s_nop 0
	v_mov_b32_e32 v244, v242
	v_mov_b32_e32 v245, v243
	v_mov_b32_e32 v248, 0x1000
	s_nop 0
	v_lshl_add_u64 v[246:247], v[248:249], 0, v[244:245]
	global_load_dwordx4 v[0:3], v[244:245], off
	global_load_dwordx4 v[4:7], v[244:245], off offset:1024
	global_load_dwordx4 v[8:11], v[244:245], off offset:2048
	global_load_dwordx4 v[12:15], v[244:245], off offset:3072
	global_load_dwordx4 v[16:19], v[246:247], off
	global_load_dwordx4 v[20:23], v[246:247], off offset:1024
	global_load_dwordx4 v[24:27], v[246:247], off offset:2048
	global_load_dwordx4 v[28:31], v[246:247], off offset:3072
	global_load_dwordx4 v[44:47], v[44:45], off
	s_nop 0
	global_load_dwordx4 v[48:51], v[48:49], off
	s_nop 0
	global_load_dwordx4 v[52:55], v[52:53], off
	s_nop 0
	global_load_dwordx4 v[56:59], v[58:59], off
	s_nop 0
	global_load_dwordx4 v[60:63], v[60:61], off
	v_readlane_b32 s56, v251, 26
	v_readlane_b32 s57, v251, 27
	v_readlane_b32 s58, v251, 28
	v_readlane_b32 s59, v251, 29
	v_readlane_b32 s60, v251, 30
	v_readlane_b32 s61, v251, 31
	v_readlane_b32 s62, v251, 32
	v_readlane_b32 s63, v251, 33
	v_readlane_b32 s64, v251, 34
	v_readlane_b32 s65, v251, 35
	v_readlane_b32 s66, v251, 36
	v_readlane_b32 s67, v251, 37
	v_readlane_b32 s20, v251, 58
	v_readlane_b32 s52, v251, 38
	v_readlane_b32 s21, v251, 59
	v_readlane_b32 s62, v251, 48
	v_readlane_b32 s63, v251, 49
	v_readlane_b32 s64, v251, 50
	v_readlane_b32 s65, v251, 51
	v_cmp_lt_u32_e64 s[0:1], 15, v72
	v_lshlrev_b32_e32 v73, 1, v71
	s_and_b64 vcc, exec, s[20:21]
	v_mov_b32_e32 v148, v143
	v_mov_b32_e32 v149, v143
	s_mov_b64 s[22:23], s[62:63]
	s_mov_b64 s[24:25], s[64:65]
	v_readlane_b32 s53, v251, 39
	v_readlane_b32 s54, v251, 40
	v_readlane_b32 s55, v251, 41
	v_readlane_b32 s56, v251, 42
	v_readlane_b32 s57, v251, 43
	v_readlane_b32 s58, v251, 44
	v_readlane_b32 s59, v251, 45
	v_readlane_b32 s60, v251, 46
	v_readlane_b32 s61, v251, 47
	v_readlane_b32 s66, v251, 52
	v_readlane_b32 s67, v251, 53
	s_cbranch_vccnz .LBB0_568
	v_add_u32_e32 v78, s41, v73
	v_ashrrev_i32_e32 v79, 31, v78
	v_lshlrev_b64 v[80:81], 6, v[78:79]
	v_or_b32_e32 v78, 1, v78
	v_readlane_b32 s42, v250, 10
	v_readlane_b32 s20, v250, 20
	v_ashrrev_i32_e32 v79, 31, v78
	v_readlane_b32 s43, v250, 11
	v_readlane_b32 s21, v250, 21
	v_lshlrev_b64 v[78:79], 6, v[78:79]
	v_lshl_add_u64 v[80:81], s[42:43], 0, v[80:81]
	s_mov_b32 s19, s21
	v_lshl_add_u64 v[78:79], s[42:43], 0, v[78:79]
	v_lshl_add_u64 v[80:81], v[80:81], 0, s[18:19]
	v_lshl_add_u64 v[78:79], v[78:79], 0, s[18:19]
	global_load_dword v148, v[80:81], off
	global_load_dword v149, v[78:79], off
.LBB0_568:
	v_writelane_b32 v250, s68, 22
	s_and_b32 s19, s68, 0x7f
	v_writelane_b32 v250, s19, 23
	v_writelane_b32 v250, s45, 24
	v_writelane_b32 v250, s44, 25
	s_lshl_b32 s19, s45, 7
	v_writelane_b32 v250, s40, 26
	v_ashrrev_i32_e32 v77, 4, v71
	s_and_b32 s87, s19, 0x3800
	s_and_b32 s19, s44, 15
	s_waitcnt vmcnt(0)
	v_mul_f32_e32 v69, 0x3fb8aa3b, v69
	v_lshlrev_b32_e32 v194, 3, v77
	v_readlane_b32 s4, v250, 5
	s_lshl_b32 s86, s44, 3
	s_and_b32 s85, s40, 7
	s_lshl_b32 s84, s19, 7
	v_exp_f32_e32 v193, v69
	v_cndmask_b32_e64 v56, 0, v56, s[6:7]
	v_cndmask_b32_e64 v57, 0, v57, s[6:7]
	v_cndmask_b32_e64 v58, 0, v58, s[6:7]
	v_cndmask_b32_e64 v59, 0, v59, s[6:7]
	v_cndmask_b32_e64 v60, 0, v60, s[6:7]
	v_cndmask_b32_e64 v61, 0, v61, s[6:7]
	v_cndmask_b32_e64 v62, 0, v62, s[6:7]
	v_cndmask_b32_e64 v63, 0, v63, s[6:7]
	v_add_u32_e32 v69, s4, v194
	v_readlane_b32 s4, v250, 10
	v_cmp_gt_i32_e64 s[6:7], 1, v71
	v_cndmask_b32_e64 v44, 0, v44, s[10:11]
	v_cndmask_b32_e64 v45, 0, v45, s[10:11]
	v_cndmask_b32_e64 v46, 0, v46, s[10:11]
	v_cndmask_b32_e64 v47, 0, v47, s[10:11]
	v_cndmask_b32_e64 v48, 0, v48, s[8:9]
	v_cndmask_b32_e64 v49, 0, v49, s[8:9]
	v_cndmask_b32_e64 v50, 0, v50, s[8:9]
	v_cndmask_b32_e64 v51, 0, v51, s[8:9]
	v_cndmask_b32_e64 v52, 0, v52, s[8:9]
	v_cndmask_b32_e64 v53, 0, v53, s[8:9]
	v_cndmask_b32_e64 v54, 0, v54, s[8:9]
	v_cndmask_b32_e64 v55, 0, v55, s[8:9]
	v_readlane_b32 s8, v250, 14
	v_readlane_b32 s5, v250, 11
	s_add_u32 s12, s4, s18
	v_readlane_b32 s90, v250, 19
	v_readlane_b32 s11, v250, 16
	v_readlane_b32 s18, v250, 17
	v_readlane_b32 s19, v250, 18
	v_readlane_b32 s10, v250, 15
	v_writelane_b32 v250, s6, 27
	v_lshlrev_b32_e32 v87, 2, v71
	s_movk_i32 s9, 0x110
	v_writelane_b32 v250, s7, 28
	v_cmp_gt_i32_e64 s[6:7], 2, v71
	v_lshlrev_b32_e32 v142, 2, v75
	s_addc_u32 s13, s5, 0
	v_writelane_b32 v250, s6, 29
	v_and_b32_e32 v196, -16, v71
	v_lshrrev_b32_e32 v79, 4, v64
	v_writelane_b32 v250, s7, 30
	v_cmp_gt_i32_e64 s[6:7], 4, v71
	v_and_b32_e32 v80, 0x78, v65
	s_add_i32 s4, 16, 0x22000
	v_writelane_b32 v250, s6, 31
	v_lshl_add_u32 v160, v72, 4, 16
	v_mul_lo_u32 v208, v66, s9
	v_writelane_b32 v250, s7, 32
; __device__ __forceinline__ u32x2 pack4(f32x4 v) { u32x2 r; r.x = cvt_pk(v[0], v[1]); r.y = cvt_pk(v[2], v[3]); return r; }
; __device__ __forceinline__ float shfl_idx_f(float v, int src) { return __int_as_float(__builtin_amdgcn_ds_bpermute(src << 2, __float_as_int(v))); }
; __device__ __forceinline__ void ssd_prompt_item(const Params& p, int item, const int wv) {
;     ...
;   const int cc = tid & 31, rg = tid >> 5;
;   const int colbc = (cc < 16) ? (1024 + g * 128 + cc * 8) : (1280 + g * 128 + (cc - 16) * 8);
;   const int xc = tid & 7, xr = tid >> 3;
;   const int colx = h * 64 + xc * 8;
;   const int j0 = rg * 8;
;   f32x4 hacc[4];
; #pragma unroll
;   for (int pb = 0; pb < 4; ++pb) hacc[pb] = (f32x4){0.f, 0.f, 0.f, 0.f};
;   u32x4 u[11], ux[5];
;   float a0 = 0.f, a1 = 0.f;
;     ...
;   SSD_PREFETCH(0);
; #pragma unroll 1
;   for (int c = 0; c < 16; ++c) {
;     const int t0 = b * 2048 + c * 128;
;     __syncthreads();
; #pragma unroll
;     for (int pb = 0; pb < 4; ++pb) *(u32x2*)(h_l + (pb * 16 + fr) * 136 + wid * 16 + fq * 4) = pack4(hacc[pb]);
;     if (wid == 0) {
;       dt_l[2 * lane] = a0; dt_l[2 * lane + 1] = a1;
;       float s = (a0 + a1) * Ah;
; #pragma unroll
;       for (int o = 1; o < 64; o <<= 1) { float v = shfl_idx_f(s, (lane - o) & 63); if (lane >= o) s += v; }
;       acum_l[2 * lane + 1] = s; acum_l[2 * lane] = s - a1 * Ah;
;     }
	v_cmp_gt_i32_e64 s[6:7], 8, v71
	v_and_b32_e32 v192, 15, v71
	v_lshl_add_u64 v[150:151], s[22:23], 0, v[142:143]
	v_writelane_b32 v250, s6, 33
	v_lshl_add_u64 v[152:153], s[24:25], 0, v[142:143]
	v_lshlrev_b32_e32 v142, 2, v76
	v_writelane_b32 v250, s7, 34
	v_cmp_gt_i32_e64 s[6:7], 16, v71
	v_lshlrev_b32_e32 v158, 2, v77
	v_lshlrev_b32_e32 v81, 1, v80
	v_writelane_b32 v250, s6, 35
	v_add_u32_e32 v82, s4, v196
	v_and_b32_e32 v64, 16, v71
	v_writelane_b32 v250, s7, 36
	s_movk_i32 s6, 0x80
	v_bitop3_b32 v207, v87, s6, v161 bitop3:0x6c
	v_cmp_gt_i32_e64 s[6:7], 32, v71
	v_cmp_gt_u32_e64 s[4:5], 16, v71
	v_mul_u32_u24_e32 v71, 0x880, v72
	v_writelane_b32 v250, s6, 37
	v_lshlrev_b32_e32 v72, 1, v66
	v_lshl_add_u64 v[154:155], s[24:25], 0, v[142:143]
	v_writelane_b32 v250, s7, 38
	s_movk_i32 s6, 0xff00
	v_add3_u32 v209, v160, v208, s6
	v_mad_u64_u32 v[168:169], s[6:7], v74, s9, v[160:161]
	v_mul_lo_u32 v74, v79, s9
	v_lshl_add_u64 v[156:157], s[22:23], 0, v[142:143]
	v_or_b32_e32 v75, s90, v192
	s_mov_b64 s[24:25], 0x4800
	v_add3_u32 v210, s19, v71, v72
	v_lshlrev_b32_e32 v72, 2, v80
	v_add3_u32 v212, s8, v81, v74
	v_add3_u32 v216, s10, v81, v74
	v_or_b32_e32 v74, 2, v158
	s_movk_i32 s6, 0x440
	v_add_u32_e32 v80, 19, v158
	v_lshl_add_u64 v[166:167], v[150:151], 0, s[24:25]
	v_lshl_add_u64 v[174:175], v[156:157], 0, s[24:25]
	v_cmp_gt_i32_e64 s[24:25], v74, v75
	v_mul_lo_u32 v74, v77, s6
	v_cmp_gt_i32_e64 s[6:7], v80, v75
	v_add_u32_e32 v79, 18, v158
	v_add_u32_e32 v211, s18, v72
	v_writelane_b32 v250, s6, 39
	v_add_u32_e32 v213, s11, v72
	v_or_b32_e32 v72, 16, v72
	v_writelane_b32 v250, s7, 40
	v_cmp_gt_i32_e64 s[6:7], v79, v75
	v_add_u32_e32 v77, 17, v158
	s_mov_b64 s[22:23], 0x3000
	v_writelane_b32 v250, s6, 41
	v_add_u32_e32 v214, s18, v72
	v_add_u32_e32 v215, s11, v72
	v_or_b32_e32 v72, 3, v158
	v_writelane_b32 v250, s7, 42
	v_cmp_gt_i32_e64 s[6:7], v77, v75
	v_lshl_add_u64 v[164:165], v[150:151], 0, s[22:23]
	v_lshl_add_u64 v[172:173], v[156:157], 0, s[22:23]
	v_cmp_gt_i32_e64 s[22:23], v72, v75
	v_add_u32_e32 v72, 16, v158
	v_writelane_b32 v250, s6, 43
	v_lshlrev_b32_e32 v85, 2, v73
	v_lshl_add_u32 v197, v75, 2, s11
	v_writelane_b32 v250, s7, 44
	v_cmp_gt_i32_e64 s[6:7], v72, v75
	v_add_u32_e32 v72, 32, v158
	v_cmp_gt_i32_e64 s[42:43], v72, v75
	v_add_u32_e32 v72, 48, v158
	v_add_u32_e32 v198, s11, v196
	v_add_u32_e32 v200, s18, v85
	v_add_u32_e32 v201, s11, v85
	v_add_u32_e32 v85, s10, v196
	v_cmp_gt_i32_e64 s[10:11], v72, v75
	v_add_u32_e32 v72, 64, v158
	v_cmp_gt_i32_e64 s[58:59], v72, v75
	v_add_u32_e32 v72, 0x50, v158
	v_cmp_gt_i32_e64 s[66:67], v72, v75
	v_add_u32_e32 v72, 0x60, v158
	v_cmp_gt_i32_e64 s[74:75], v72, v75
	v_add_u32_e32 v72, 0x70, v158
	v_add_u32_e32 v68, s87, v68
	v_lshl_or_b32 v142, v67, 1, s84
	v_cmp_gt_i32_e64 s[82:83], v72, v75
	v_add_u32_e32 v217, s87, v73
	v_mad_i64_i32 v[72:73], s[88:89], v68, s33, v[142:143]
	v_mul_u32_u24_e32 v71, 0x110, v67
	s_mov_b64 s[88:89], 0x730e000
	v_add_u32_e32 v67, 0x80, v68
	v_writelane_b32 v250, s6, 45
	v_add_u32_e32 v80, 35, v158
	v_lshl_add_u64 v[176:177], v[72:73], 0, s[88:89]
	v_mad_i64_i32 v[72:73], s[88:89], v67, s33, v[142:143]
	v_add_u32_e32 v67, 0x7e, v68
	v_writelane_b32 v250, s7, 46
	v_cmp_gt_i32_e64 s[6:7], v80, v75
	s_mov_b64 s[92:93], 0x72aec00
	v_mad_i64_i32 v[180:181], s[88:89], v67, s33, v[142:143]
	v_add_u32_e32 v67, 0x7c, v68
	s_add_i32 s41, s90, s41
	v_add_u32_e32 v79, 34, v158
	v_writelane_b32 v250, s6, 47
	v_lshl_add_u64 v[178:179], v[72:73], 0, s[92:93]
	v_mad_i64_i32 v[72:73], s[88:89], v67, s33, v[142:143]
	v_add_u32_e32 v142, s41, v192
	v_writelane_b32 v250, s7, 48
	v_cmp_gt_i32_e64 s[6:7], v79, v75
	v_lshlrev_b64 v[184:185], 7, v[142:143]
	v_add_u32_e32 v77, 33, v158
	v_writelane_b32 v250, s6, 49
	v_add_u32_e32 v218, s87, v66
	v_and_or_b32 v66, s86, 64, v184
	v_writelane_b32 v250, s7, 50
	v_cmp_gt_i32_e64 s[6:7], v77, v75
	v_lshl_or_b32 v184, s85, 3, v66
	v_lshlrev_b64 v[66:67], 11, v[142:143]
	v_ashrrev_i32_e32 v159, 31, v158
	v_and_b32_e32 v65, -8, v158
	v_add_u32_e32 v88, 0xfc, v87
	v_writelane_b32 v250, s6, 51
	v_add_u32_e32 v77, 49, v158
	v_add_u32_e32 v79, 50, v158
	v_add_u32_e32 v80, 51, v158
	v_or_b32_e32 v66, s84, v66
	v_lshl_add_u32 v70, v70, 2, s8
	v_mul_lo_u32 v76, v75, s9
	v_add_u32_e32 v83, s8, v196
	v_lshl_add_u32 v84, v75, 1, s8
	v_add_u32_e32 v64, v65, v64
	v_and_b32_e32 v202, 0xfc, v88
	v_add_u32_e32 v88, 0xf8, v87
	v_writelane_b32 v250, s7, 52
	v_cmp_gt_i32_e64 s[44:45], v80, v75
	v_cmp_gt_i32_e64 s[6:7], v79, v75
	v_cmp_gt_i32_e64 s[8:9], v77, v75
	v_add_u32_e32 v77, 0x41, v158
	v_add_u32_e32 v79, 0x42, v158
	v_add_u32_e32 v80, 0x43, v158
	v_lshl_add_u64 v[182:183], v[72:73], 0, s[92:93]
	v_lshl_add_u64 v[72:73], v[158:159], 1, v[66:67]
	s_mov_b64 s[84:85], 0x526e040
	v_ashrrev_i32_e32 v65, 31, v64
	v_and_b32_e32 v203, 0xfc, v88
	v_add_u32_e32 v88, 0xf0, v87
	v_cmp_gt_i32_e64 s[52:53], v80, v75
	v_cmp_gt_i32_e64 s[54:55], v79, v75
	v_cmp_gt_i32_e64 s[56:57], v77, v75
	v_add_u32_e32 v77, 0x51, v158
	v_add_u32_e32 v79, 0x52, v158
	v_add_u32_e32 v80, 0x53, v158
	v_lshl_add_u64 v[186:187], v[72:73], 0, s[84:85]
	v_readlane_b32 s84, v250, 12
	v_and_b32_e32 v204, 0xfc, v88
	v_add_u32_e32 v88, 0xe0, v87
	v_cmp_gt_i32_e64 s[60:61], v80, v75
	v_cmp_gt_i32_e64 s[62:63], v79, v75
	v_cmp_gt_i32_e64 s[64:65], v77, v75
	v_add_u32_e32 v77, 0x61, v158
	v_add_u32_e32 v79, 0x62, v158
	v_add_u32_e32 v80, 0x63, v158
	v_lshl_add_u64 v[64:65], v[64:65], 1, v[66:67]
	v_readlane_b32 s85, v250, 13
	v_add_u32_e32 v195, 16, v76
	v_add_u32_e32 v78, 16, v196
	v_add_u32_e32 v76, s19, v76
	v_mul_u32_u24_e32 v86, 0x110, v192
	v_and_b32_e32 v205, 0xfc, v88
	v_add_u32_e32 v88, 0xc0, v87
	s_mov_b64 s[20:21], 0x1800
	v_cmp_gt_i32_e64 s[68:69], v80, v75
	v_cmp_gt_i32_e64 s[70:71], v79, v75
	v_cmp_gt_i32_e64 s[72:73], v77, v75
	v_add_u32_e32 v77, 0x71, v158
	v_add_u32_e32 v79, 0x72, v158
	v_add_u32_e32 v80, 0x73, v158
	v_lshl_add_u64 v[188:189], s[84:85], 0, v[64:65]
	v_mov_b32_e32 v64, 0
	s_mov_b32 s40, 0
	v_add_u32_e32 v199, s18, v196
	v_and_b32_e32 v206, 0xfc, v88
	v_lshl_add_u64 v[162:163], v[150:151], 0, s[20:21]
	v_add_u32_e32 v169, 0xffffff00, v168
	v_lshl_add_u64 v[170:171], v[156:157], 0, s[20:21]
	v_cmp_gt_i32_e64 s[18:19], v158, v75
	v_cmp_lt_i32_e64 s[20:21], v158, v75
	v_mov_b32_e32 v145, v144
	v_cmp_gt_i32_e64 s[76:77], v80, v75
	v_cmp_gt_i32_e64 s[78:79], v79, v75
	v_cmp_gt_i32_e64 s[80:81], v77, v75
	v_add_u32_e32 v219, v69, v86
	v_add_u32_e32 v220, v70, v71
	v_add_u32_e32 v221, v76, v196
	v_add_u32_e32 v222, v85, v86
	v_add_u32_e32 v223, v78, v86
	v_add_u32_e32 v224, v82, v86
	v_add_u32_e32 v225, v83, v86
	v_add_u32_e32 v226, v84, v74
	v_mov_b32_e32 v65, v64
	v_mov_b32_e32 v66, v64
	v_mov_b32_e32 v67, v64
	v_mov_b32_e32 v76, v64
	v_mov_b32_e32 v77, v64
	v_mov_b32_e32 v78, v64
	v_mov_b32_e32 v79, v64
	v_mov_b32_e32 v72, v64
	v_mov_b32_e32 v73, v64
	v_mov_b32_e32 v74, v64
	v_mov_b32_e32 v75, v64
	v_mov_b32_e32 v68, v64
	v_mov_b32_e32 v69, v64
	v_mov_b32_e32 v70, v64
	v_mov_b32_e32 v71, v64
	s_branch .LBB0_570

; __device__ __forceinline__ unsigned cvt_pk(float lo, float hi) { f32x2 v = {lo, hi}; bf16x2_t b = __builtin_convertvector(v, bf16x2_t); return __builtin_bit_cast(unsigned, b); }
; __device__ __forceinline__ float bflo(unsigned w) { return __uint_as_float(w << 16); }
; __device__ __forceinline__ float bfhi(unsigned w) { return __uint_as_float(w & 0xffff0000u); }
; __device__ __forceinline__ void ssd_prompt_item(const Params& p, int item, const int wv) {
;     ...
;       unsigned outp[8][4];
; #pragma unroll
;       for (int jj = 0; jj < 8; ++jj) {
;         float o[8];
; #pragma unroll
;         for (int e = 0; e < 8; ++e) o[e] = bias[e];
; #pragma unroll
;         for (int k = 0; k < 4; ++k) {
;           u32x4 uu = u[jj + k];
;           o[0] += w[k][0] * bflo(uu.x); o[1] += w[k][1] * bfhi(uu.x); o[2] += w[k][2] * bflo(uu.y); o[3] += w[k][3] * bfhi(uu.y);
;           o[4] += w[k][4] * bflo(uu.z); o[5] += w[k][5] * bfhi(uu.z); o[6] += w[k][6] * bflo(uu.w); o[7] += w[k][7] * bfhi(uu.w);
;         }
; #pragma unroll
;         for (int e = 0; e < 8; ++e) o[e] = silu_f(o[e]);
; #pragma unroll
;         for (int e2 = 0; e2 < 4; ++e2) outp[jj][e2] = cvt_pk(o[2 * e2], o[2 * e2 + 1]);
;       }
;       if (cc < 16) {
; #pragma unroll
;         for (int jj = 0; jj < 8; ++jj) *(u32x4*)(B_l + (j0 + jj) * 136 + cc * 8) = (u32x4){outp[jj][0], outp[jj][1], outp[jj][2], outp[jj][3]};
; #pragma unroll
;         for (int e2 = 0; e2 < 4; ++e2) {
;           u32x4 lo, hi;
;           lo.x = (outp[0][e2] & 0xffffu) | (outp[1][e2] << 16); lo.y = (outp[2][e2] & 0xffffu) | (outp[3][e2] << 16);
;           lo.z = (outp[4][e2] & 0xffffu) | (outp[5][e2] << 16); lo.w = (outp[6][e2] & 0xffffu) | (outp[7][e2] << 16);
;           hi.x = (outp[0][e2] >> 16) | (outp[1][e2] & 0xffff0000u); hi.y = (outp[2][e2] >> 16) | (outp[3][e2] & 0xffff0000u);
;           hi.z = (outp[4][e2] >> 16) | (outp[5][e2] & 0xffff0000u); hi.w = (outp[6][e2] >> 16) | (outp[7][e2] & 0xffff0000u);
;           *(u32x4*)(BT_l + (cc * 8 + 2 * e2) * 136 + j0) = lo;
;           *(u32x4*)(BT_l + (cc * 8 + 2 * e2 + 1) * 136 + j0) = hi;
;         }
;       } else {
; #pragma unroll
;         for (int jj = 0; jj < 8; ++jj) *(u32x4*)(C_l + (j0 + jj) * 136 + (cc - 16) * 8) = (u32x4){outp[jj][0], outp[jj][1], outp[jj][2], outp[jj][3]};
;       }
.LBB0_572:
	v_mov_b32_e32 v84, v0
	v_mov_b32_e32 v85, v1
	v_mov_b32_e32 v86, v2
	v_mov_b32_e32 v87, v3
	v_mov_b32_e32 v80, v4
	v_mov_b32_e32 v81, v5
	v_mov_b32_e32 v82, v6
	v_mov_b32_e32 v83, v7
	v_mov_b32_e32 v88, v8
	v_mov_b32_e32 v89, v9
	v_mov_b32_e32 v90, v10
	v_mov_b32_e32 v91, v11
	v_mov_b32_e32 v92, v12
	v_mov_b32_e32 v93, v13
	v_mov_b32_e32 v94, v14
	v_mov_b32_e32 v95, v15
	v_mov_b32_e32 v96, v16
	v_mov_b32_e32 v97, v17
	v_mov_b32_e32 v98, v18
	v_mov_b32_e32 v99, v19
	v_mov_b32_e32 v100, v20
	v_mov_b32_e32 v101, v21
	v_mov_b32_e32 v102, v22
	v_mov_b32_e32 v103, v23
	v_mov_b32_e32 v104, v24
	v_mov_b32_e32 v105, v25
	v_mov_b32_e32 v106, v26
	v_mov_b32_e32 v107, v27
	v_mov_b32_e32 v108, v28
	v_mov_b32_e32 v109, v29
	v_mov_b32_e32 v110, v30
	v_mov_b32_e32 v111, v31
	v_add_u32_e32 v112, v160, v208
	s_and_saveexec_b64 s[84:85], s[0:1]
	s_xor_b64 s[84:85], exec, s[84:85]
	s_cbranch_execz .LBB0_574
	ds_write_b128 v209, v[84:87]
	ds_write_b128 v112, v[80:83] offset:16
	ds_write_b128 v112, v[88:91] offset:288
	ds_write_b128 v112, v[92:95] offset:560
	ds_write_b128 v112, v[96:99] offset:832
	ds_write_b128 v112, v[100:103] offset:1104
	ds_write_b128 v112, v[104:107] offset:1376
	ds_write_b128 v169, v[108:111]

; __device__ __forceinline__ unsigned cvt_pk(float lo, float hi) { f32x2 v = {lo, hi}; bf16x2_t b = __builtin_convertvector(v, bf16x2_t); return __builtin_bit_cast(unsigned, b); }
; __device__ __forceinline__ float bflo(unsigned w) { return __uint_as_float(w << 16); }
; __device__ __forceinline__ float bfhi(unsigned w) { return __uint_as_float(w & 0xffff0000u); }
; __device__ __forceinline__ float silu_f(float x) { return x * __builtin_amdgcn_rcpf(1.f + __builtin_amdgcn_exp2f(-1.4426950409f * x)); }
; __device__ __forceinline__ void ssd_prompt_item(const Params& p, int item, const int wv) {
;     ...
;     {
;       f32x4 b0 = *(const f32x4*)(convb + colx), b1 = *(const f32x4*)(convb + colx + 4);
;       f32x4 w0[4], w1[4];
; #pragma unroll
;       for (int k = 0; k < 4; ++k) { w0[k] = *(const f32x4*)(convw + k * 1536 + colx); w1[k] = *(const f32x4*)(convw + k * 1536 + colx + 4); }
;       float xo[2][8];
; #pragma unroll
;       for (int r2 = 0; r2 < 2; ++r2) {
;         float o[8] = {b0[0], b0[1], b0[2], b0[3], b1[0], b1[1], b1[2], b1[3]};
; #pragma unroll
;         for (int k = 0; k < 4; ++k) {
;           u32x4 uu = ux[r2 + k];
;           o[0] += w0[k][0] * bflo(uu.x); o[1] += w0[k][1] * bfhi(uu.x); o[2] += w0[k][2] * bflo(uu.y); o[3] += w0[k][3] * bfhi(uu.y);
;           o[4] += w1[k][0] * bflo(uu.z); o[5] += w1[k][1] * bfhi(uu.z); o[6] += w1[k][2] * bflo(uu.w); o[7] += w1[k][3] * bfhi(uu.w);
;         }
; #pragma unroll
;         for (int e = 0; e < 8; ++e) xo[r2][e] = silu_f(o[e]);
;       }
; #pragma unroll
;       for (int e = 0; e < 8; ++e) *(unsigned*)(xT_l + (xc * 8 + e) * 136 + 2 * xr) = cvt_pk(xo[0][e], xo[1][e]);
.LBB0_576:
	s_or_b64 exec, exec, s[84:85]
	global_load_dwordx4 v[80:83], v[154:155], off offset:16
	global_load_dwordx4 v[100:103], v[154:155], off
	global_load_dwordx4 v[84:87], v[156:157], off offset:16
	global_load_dwordx4 v[104:107], v[156:157], off
	global_load_dwordx4 v[88:91], v[170:171], off offset:16
	global_load_dwordx4 v[108:111], v[170:171], off
	global_load_dwordx4 v[92:95], v[172:173], off offset:16
	global_load_dwordx4 v[112:115], v[172:173], off
	global_load_dwordx4 v[96:99], v[174:175], off offset:16
	global_load_dwordx4 v[116:119], v[174:175], off
	v_lshlrev_b32_e32 v120, 16, v44
	v_lshlrev_b32_e32 v121, 16, v48
	v_lshlrev_b32_e32 v123, 16, v52
	v_mov_b32_e32 v122, v121
	v_lshlrev_b32_e32 v127, 16, v56
	v_mov_b32_e32 v126, v123
	v_lshlrev_b32_e32 v125, 16, v60
	v_mov_b32_e32 v124, v127
	v_and_b32_e32 v129, 0xffff0000, v60
	s_cmpk_eq_i32 s40, 0x780
	s_waitcnt vmcnt(6)
	v_pk_fma_f32 v[120:121], v[104:105], v[120:121], v[100:101] op_sel_hi:[0,1,0]
	s_waitcnt vmcnt(4)
	v_pk_fma_f32 v[120:121], v[108:109], v[122:123], v[120:121] op_sel_hi:[0,1,1]
	s_waitcnt vmcnt(2)
	v_pk_fma_f32 v[120:121], v[112:113], v[126:127], v[120:121] op_sel_hi:[0,1,1]
	v_and_b32_e32 v127, 0xffff0000, v56
	s_waitcnt vmcnt(0)
	v_pk_fma_f32 v[120:121], v[116:117], v[124:125], v[120:121] op_sel_hi:[0,1,1]
	v_mul_f32_e32 v122, 0xbfb8aa3b, v120
	v_mul_f32_e32 v123, 0xbfb8aa3b, v121
	v_exp_f32_e32 v122, v122
	v_exp_f32_e32 v123, v123
	v_and_b32_e32 v125, 0xffff0000, v52
	v_mov_b32_e32 v126, v125
	v_add_f32_e32 v122, 1.0, v122
	v_add_f32_e32 v123, 1.0, v123
	v_rcp_f32_e32 v122, v122
	v_rcp_f32_e32 v123, v123
	v_mov_b32_e32 v128, v127
	v_pk_mul_f32 v[120:121], v[120:121], v[122:123]
	v_and_b32_e32 v123, 0xffff0000, v48
	v_and_b32_e32 v122, 0xffff0000, v44
	v_mov_b32_e32 v124, v123
	v_pk_fma_f32 v[100:101], v[104:105], v[122:123], v[100:101] op_sel:[1,0,1]
	v_and_b32_e32 v123, 0xffff0000, v61
	v_pk_fma_f32 v[100:101], v[108:109], v[124:125], v[100:101] op_sel:[1,0,0]
	v_lshlrev_b32_e32 v109, 16, v53
	v_pk_fma_f32 v[100:101], v[112:113], v[126:127], v[100:101] op_sel:[1,0,0]
	v_lshlrev_b32_e32 v113, 16, v61
	v_pk_fma_f32 v[100:101], v[116:117], v[128:129], v[100:101] op_sel:[1,0,0]
	v_lshlrev_b32_e32 v117, 16, v57
	v_mul_f32_e32 v104, 0xbfb8aa3b, v100
	v_mul_f32_e32 v105, 0xbfb8aa3b, v101
	v_exp_f32_e32 v104, v104
	v_exp_f32_e32 v105, v105
	v_mov_b32_e32 v116, v109
	v_mov_b32_e32 v112, v117
	v_add_f32_e32 v104, 1.0, v104
	v_add_f32_e32 v105, 1.0, v105
	v_rcp_f32_e32 v104, v104
	v_rcp_f32_e32 v105, v105
	s_nop 0
	v_pk_mul_f32 v[100:101], v[100:101], v[104:105]
	v_lshlrev_b32_e32 v104, 16, v45
	v_lshlrev_b32_e32 v105, 16, v49
	v_mov_b32_e32 v108, v105
	v_pk_fma_f32 v[104:105], v[106:107], v[104:105], v[102:103] op_sel_hi:[0,1,0]
	v_pk_fma_f32 v[104:105], v[110:111], v[108:109], v[104:105] op_sel_hi:[0,1,1]
	v_pk_fma_f32 v[104:105], v[114:115], v[116:117], v[104:105] op_sel_hi:[0,1,1]
	v_pk_fma_f32 v[104:105], v[118:119], v[112:113], v[104:105] op_sel_hi:[0,1,1]
	v_mul_f32_e32 v102, 0xbfb8aa3b, v104
	v_exp_f32_e32 v102, v102
	v_mov_b32_e32 v106, v103
	v_and_b32_e32 v113, 0xffff0000, v53
	v_and_b32_e32 v117, 0xffff0000, v57
	v_add_f32_e32 v102, 1.0, v102
	v_rcp_f32_e32 v108, v102
	v_mul_f32_e32 v102, 0xbfb8aa3b, v105
	v_exp_f32_e32 v102, v102
	v_mov_b32_e32 v116, v113
	v_mov_b32_e32 v122, v117
	v_add_f32_e32 v102, 1.0, v102
	v_rcp_f32_e32 v109, v102
	v_mov_b32_e32 v102, v107
	v_pk_mul_f32 v[104:105], v[104:105], v[108:109]
	v_and_b32_e32 v109, 0xffff0000, v49
	v_and_b32_e32 v108, 0xffff0000, v45
	v_mov_b32_e32 v112, v109
	v_pk_fma_f32 v[102:103], v[102:103], v[108:109], v[106:107] op_sel_hi:[0,1,0]
	v_mov_b32_e32 v106, v111
	v_pk_fma_f32 v[102:103], v[106:107], v[112:113], v[102:103] op_sel_hi:[0,1,1]
	v_mov_b32_e32 v106, v115
	v_pk_fma_f32 v[102:103], v[106:107], v[116:117], v[102:103] op_sel_hi:[0,1,1]
	v_mov_b32_e32 v106, v119
	v_pk_fma_f32 v[102:103], v[106:107], v[122:123], v[102:103] op_sel_hi:[0,1,1]
	v_mul_f32_e32 v106, 0xbfb8aa3b, v102
	v_mul_f32_e32 v107, 0xbfb8aa3b, v103
	v_exp_f32_e32 v106, v106
	v_exp_f32_e32 v107, v107
	v_lshlrev_b32_e32 v109, 16, v54
	v_lshlrev_b32_e32 v113, 16, v58
	v_add_f32_e32 v106, 1.0, v106
	v_add_f32_e32 v107, 1.0, v107
	v_rcp_f32_e32 v106, v106
	v_rcp_f32_e32 v107, v107
	v_mov_b32_e32 v112, v109
	v_lshlrev_b32_e32 v111, 16, v62
	v_mov_b32_e32 v110, v113
	v_pk_mul_f32 v[102:103], v[102:103], v[106:107]
	v_lshlrev_b32_e32 v106, 16, v46
	v_lshlrev_b32_e32 v107, 16, v50
	v_mov_b32_e32 v108, v107
	v_pk_fma_f32 v[106:107], v[84:85], v[106:107], v[80:81] op_sel_hi:[0,1,0]
	v_pk_fma_f32 v[106:107], v[88:89], v[108:109], v[106:107] op_sel_hi:[0,1,1]
	v_pk_fma_f32 v[106:107], v[92:93], v[112:113], v[106:107] op_sel_hi:[0,1,1]
	v_pk_fma_f32 v[106:107], v[96:97], v[110:111], v[106:107] op_sel_hi:[0,1,1]
	v_mul_f32_e32 v108, 0xbfb8aa3b, v106
	v_mul_f32_e32 v109, 0xbfb8aa3b, v107
	v_exp_f32_e32 v108, v108
	v_exp_f32_e32 v109, v109
	v_and_b32_e32 v111, 0xffff0000, v54
	v_and_b32_e32 v113, 0xffff0000, v58
	v_add_f32_e32 v108, 1.0, v108
; __device__ __forceinline__ unsigned cvt_pk(float lo, float hi) { f32x2 v = {lo, hi}; bf16x2_t b = __builtin_convertvector(v, bf16x2_t); return __builtin_bit_cast(unsigned, b); }
; __device__ __forceinline__ float bflo(unsigned w) { return __uint_as_float(w << 16); }
; __device__ __forceinline__ float bfhi(unsigned w) { return __uint_as_float(w & 0xffff0000u); }
; __device__ __forceinline__ float silu_f(float x) { return x * __builtin_amdgcn_rcpf(1.f + __builtin_amdgcn_exp2f(-1.4426950409f * x)); }
; __device__ __forceinline__ void ssd_prompt_item(const Params& p, int item, const int wv) {
;     ...
;     {
;       f32x4 b0 = *(const f32x4*)(convb + colx), b1 = *(const f32x4*)(convb + colx + 4);
;       f32x4 w0[4], w1[4];
; #pragma unroll
;       for (int k = 0; k < 4; ++k) { w0[k] = *(const f32x4*)(convw + k * 1536 + colx); w1[k] = *(const f32x4*)(convw + k * 1536 + colx + 4); }
;       float xo[2][8];
; #pragma unroll
;       for (int r2 = 0; r2 < 2; ++r2) {
;         float o[8] = {b0[0], b0[1], b0[2], b0[3], b1[0], b1[1], b1[2], b1[3]};
; #pragma unroll
;         for (int k = 0; k < 4; ++k) {
;           u32x4 uu = ux[r2 + k];
;           o[0] += w0[k][0] * bflo(uu.x); o[1] += w0[k][1] * bfhi(uu.x); o[2] += w0[k][2] * bflo(uu.y); o[3] += w0[k][3] * bfhi(uu.y);
;           o[4] += w1[k][0] * bflo(uu.z); o[5] += w1[k][1] * bfhi(uu.z); o[6] += w1[k][2] * bflo(uu.w); o[7] += w1[k][3] * bfhi(uu.w);
;         }
; #pragma unroll
;         for (int e = 0; e < 8; ++e) xo[r2][e] = silu_f(o[e]);
;       }
; #pragma unroll
;       for (int e = 0; e < 8; ++e) *(unsigned*)(xT_l + (xc * 8 + e) * 136 + 2 * xr) = cvt_pk(xo[0][e], xo[1][e]);
;     }
;     __syncthreads();
;     if (c < 15) SSD_PREFETCH(c + 1);
	v_add_f32_e32 v109, 1.0, v109
	v_rcp_f32_e32 v108, v108
	v_rcp_f32_e32 v109, v109
	v_mov_b32_e32 v112, v111
	v_and_b32_e32 v115, 0xffff0000, v62
	v_mov_b32_e32 v114, v113
	v_pk_mul_f32 v[106:107], v[106:107], v[108:109]
	v_and_b32_e32 v109, 0xffff0000, v50
	v_and_b32_e32 v108, 0xffff0000, v46
	v_mov_b32_e32 v110, v109
	v_pk_fma_f32 v[80:81], v[84:85], v[108:109], v[80:81] op_sel:[1,0,1]
	v_and_b32_e32 v109, 0xffff0000, v63
	v_pk_fma_f32 v[80:81], v[88:89], v[110:111], v[80:81] op_sel:[1,0,0]
	v_lshlrev_b32_e32 v89, 16, v55
	v_pk_fma_f32 v[80:81], v[92:93], v[112:113], v[80:81] op_sel:[1,0,0]
	v_lshlrev_b32_e32 v93, 16, v63
	v_pk_fma_f32 v[80:81], v[96:97], v[114:115], v[80:81] op_sel:[1,0,0]
	v_lshlrev_b32_e32 v97, 16, v59
	v_mul_f32_e32 v84, 0xbfb8aa3b, v80
	v_mul_f32_e32 v85, 0xbfb8aa3b, v81
	v_exp_f32_e32 v84, v84
	v_exp_f32_e32 v85, v85
	v_mov_b32_e32 v96, v89
	v_mov_b32_e32 v92, v97
	v_add_f32_e32 v84, 1.0, v84
	v_add_f32_e32 v85, 1.0, v85
	v_rcp_f32_e32 v84, v84
	v_rcp_f32_e32 v85, v85
	s_nop 0
	v_pk_mul_f32 v[80:81], v[80:81], v[84:85]
	v_lshlrev_b32_e32 v84, 16, v47
	v_lshlrev_b32_e32 v85, 16, v51
	v_mov_b32_e32 v88, v85
	v_pk_fma_f32 v[84:85], v[86:87], v[84:85], v[82:83] op_sel_hi:[0,1,0]
	v_pk_fma_f32 v[84:85], v[90:91], v[88:89], v[84:85] op_sel_hi:[0,1,1]
	v_pk_fma_f32 v[84:85], v[94:95], v[96:97], v[84:85] op_sel_hi:[0,1,1]
	v_pk_fma_f32 v[84:85], v[98:99], v[92:93], v[84:85] op_sel_hi:[0,1,1]
	v_mul_f32_e32 v82, 0xbfb8aa3b, v84
	v_exp_f32_e32 v82, v82
	v_mov_b32_e32 v86, v83
	v_and_b32_e32 v93, 0xffff0000, v55
	v_and_b32_e32 v97, 0xffff0000, v59
	v_add_f32_e32 v82, 1.0, v82
	v_rcp_f32_e32 v88, v82
	v_mul_f32_e32 v82, 0xbfb8aa3b, v85
	v_exp_f32_e32 v82, v82
	v_mov_b32_e32 v96, v93
	v_mov_b32_e32 v108, v97
	v_cvt_pk_bf16_f32 v80, v80, v81
	v_add_f32_e32 v82, 1.0, v82
	v_rcp_f32_e32 v89, v82
	v_mov_b32_e32 v82, v87
	v_add_u32_e32 v81, 0x400, v220
	v_pk_mul_f32 v[84:85], v[84:85], v[88:89]
	v_and_b32_e32 v89, 0xffff0000, v51
	v_and_b32_e32 v88, 0xffff0000, v47
	v_mov_b32_e32 v92, v89
	v_pk_fma_f32 v[82:83], v[82:83], v[88:89], v[86:87] op_sel_hi:[0,1,0]
	v_mov_b32_e32 v86, v91
	v_pk_fma_f32 v[82:83], v[86:87], v[92:93], v[82:83] op_sel_hi:[0,1,1]
	v_mov_b32_e32 v86, v95
	v_pk_fma_f32 v[82:83], v[86:87], v[96:97], v[82:83] op_sel_hi:[0,1,1]
	v_mov_b32_e32 v86, v99
	v_pk_fma_f32 v[82:83], v[86:87], v[108:109], v[82:83] op_sel_hi:[0,1,1]
	v_mul_f32_e32 v86, 0xbfb8aa3b, v82
	v_mul_f32_e32 v87, 0xbfb8aa3b, v83
	v_exp_f32_e32 v86, v86
	v_exp_f32_e32 v87, v87
	v_add_f32_e32 v86, 1.0, v86
	v_add_f32_e32 v87, 1.0, v87
	v_rcp_f32_e32 v86, v86
	v_rcp_f32_e32 v87, v87
	s_nop 0
	v_pk_mul_f32 v[82:83], v[82:83], v[86:87]
	v_cvt_pk_bf16_f32 v86, v120, v121
	v_cvt_pk_bf16_f32 v87, v100, v101
	ds_write2_b32 v220, v86, v87 offset1:68
	v_cvt_pk_bf16_f32 v86, v104, v105
	v_cvt_pk_bf16_f32 v87, v102, v103
	ds_write2_b32 v220, v86, v87 offset0:136 offset1:204
	v_cvt_pk_bf16_f32 v86, v106, v107
	ds_write2_b32 v81, v86, v80 offset0:16 offset1:84
	v_cvt_pk_bf16_f32 v80, v84, v85
	v_cvt_pk_bf16_f32 v82, v82, v83
	ds_write2_b32 v81, v80, v82 offset0:152 offset1:220
	s_waitcnt lgkmcnt(0)
	s_barrier
	s_cbranch_scc1 .LBB0_579
	v_add_u32_e32 v40, s40, v218
	v_lshl_add_u64 v[48:49], s[50:51], 0, v[180:181]
	v_add_co_u32_e32 v52, vcc, 0x72ae000, v48
	v_lshl_add_u64 v[44:45], s[50:51], 0, v[182:183]
	v_addc_co_u32_e32 v53, vcc, 0, v49, vcc
	v_lshl_add_u64 v[56:57], s[50:51], 0, v[176:177]
	v_lshl_add_u64 v[60:61], s[50:51], 0, v[178:179]
	s_nop 0
	s_nop 0
	s_nop 0
	s_nop 0
	s_nop 0
	s_nop 0
	s_nop 0
	s_nop 0
	s_nop 0
	s_nop 0
	s_nop 0
	s_add_u32 s84, s40, 0x80
	s_lshl_b32 s84, s84, 10
	v_mov_b32_e32 v248, s84
	s_nop 0
	v_lshl_add_u64 v[244:245], v[248:249], 0, v[242:243]
	v_mov_b32_e32 v248, 0x1000
	s_nop 0
	v_lshl_add_u64 v[246:247], v[248:249], 0, v[244:245]
	global_load_dwordx4 v[0:3], v[244:245], off
	global_load_dwordx4 v[4:7], v[244:245], off offset:1024
	global_load_dwordx4 v[8:11], v[244:245], off offset:2048
	global_load_dwordx4 v[12:15], v[244:245], off offset:3072
	global_load_dwordx4 v[16:19], v[246:247], off
	global_load_dwordx4 v[20:23], v[246:247], off offset:1024
	global_load_dwordx4 v[24:27], v[246:247], off offset:2048
	global_load_dwordx4 v[28:31], v[246:247], off offset:3072
	global_load_dwordx4 v[44:47], v[44:45], off
	s_nop 0
	global_load_dwordx4 v[48:51], v[52:53], off
	s_nop 0
	global_load_dwordx4 v[52:55], v[52:53], off offset:3072
	s_nop 0
	global_load_dwordx4 v[56:59], v[56:57], off
	s_nop 0
	global_load_dwordx4 v[60:63], v[60:61], off
	v_readlane_b32 s84, v251, 58
	v_readlane_b32 s85, v251, 59
	s_and_b64 vcc, exec, s[84:85]
	s_cbranch_vccnz .LBB0_579
	v_add_u32_e32 v82, s40, v217
	v_add_u32_e32 v80, 0x80, v82
	v_ashrrev_i32_e32 v81, 31, v80
	v_lshlrev_b64 v[80:81], 6, v[80:81]
	v_lshl_add_u64 v[80:81], s[12:13], 0, v[80:81]
	global_load_dword v148, v[80:81], off
	v_add_u32_e32 v80, 0x81, v82
	v_ashrrev_i32_e32 v81, 31, v80
	v_lshlrev_b64 v[80:81], 6, v[80:81]
	v_lshl_add_u64 v[80:81], s[12:13], 0, v[80:81]
	global_load_dword v149, v[80:81], off
